# PEER pass1: hoisted expert-index, per-head scale/gate and first-head row loads with recomputed vmcnt waits (on top of batched-load fixes)
# speedup vs baseline: 1.0632x; 1.0089x over previous
.LBB0_538:
	v_cmp_gt_i32_e32 vcc, s33, v2
	s_or_b64 s[16:17], s[16:17], exec
	s_and_saveexec_b64 s[18:19], vcc
	s_cbranch_execz .LBB0_537
	v_ashrrev_i32_e32 v3, 31, v2
	v_lshlrev_b64 v[4:5], 11, v[2:3]
	v_lshl_add_u64 v[8:9], v[60:61], 0, v[4:5]
	global_load_dwordx4 v[4:7], v[8:9], off offset:16
	s_nop 0
	global_load_dwordx4 v[8:11], v[8:9], off
	v_lshlrev_b64 v[110:111], 9, v[2:3]
	v_lshl_add_u64 v[110:111], v[62:63], 0, v[110:111]
	global_load_dword v112, v[110:111], off
	global_load_dword v113, v[110:111], off offset:64
	global_load_dword v114, v[110:111], off offset:128
	global_load_dword v115, v[110:111], off offset:192
	global_load_dword v116, v[110:111], off offset:256
	global_load_dword v117, v[110:111], off offset:320
	global_load_dword v118, v[110:111], off offset:384
	global_load_dword v119, v[110:111], off offset:448
	s_waitcnt lgkmcnt(0)
	v_add_u32_e32 v109, s20, v193
	s_waitcnt vmcnt(9)
	v_lshlrev_b32_e32 v13, 16, v4
	s_waitcnt vmcnt(8)
	v_lshlrev_b32_e32 v12, 16, v8
	v_and_b32_e32 v8, 0xffff0000, v8
	v_lshlrev_b32_e32 v14, 16, v9
	v_and_b32_e32 v15, 0xffff0000, v9
	v_max3_f32 v0, |v12|, 0, |v8|
	v_lshlrev_b32_e32 v17, 16, v10
	v_and_b32_e32 v10, 0xffff0000, v10
	v_max3_f32 v0, v0, |v14|, |v15|
	v_lshlrev_b32_e32 v19, 16, v11
	v_and_b32_e32 v11, 0xffff0000, v11
	v_max3_f32 v0, v0, |v17|, |v10|
	v_and_b32_e32 v4, 0xffff0000, v4
	v_max3_f32 v0, v0, |v19|, |v11|
	v_lshlrev_b32_e32 v16, 16, v5
	v_and_b32_e32 v5, 0xffff0000, v5
	v_max3_f32 v0, v0, |v13|, |v4|
	v_lshlrev_b32_e32 v18, 16, v6
	v_and_b32_e32 v6, 0xffff0000, v6
	v_max3_f32 v0, v0, |v16|, |v5|
	v_lshlrev_b32_e32 v20, 16, v7
	v_and_b32_e32 v7, 0xffff0000, v7
	v_max3_f32 v0, v0, |v18|, |v6|
	v_max3_f32 v9, v0, |v20|, |v7|
	v_and_b32_e32 v0, 64, v219
	v_add_u32_e32 v21, 64, v0
	v_xor_b32_e32 v0, 32, v219
	v_cmp_lt_i32_e32 vcc, v0, v21
	s_nop 1
	v_cndmask_b32_e32 v0, v219, v0, vcc
	v_lshlrev_b32_e32 v0, 2, v0
	ds_bpermute_b32 v22, v0, v9
	s_waitcnt lgkmcnt(0)
	v_max_f32_e32 v22, v22, v22
	v_max_f32_e32 v9, v9, v22
	v_xor_b32_e32 v22, 16, v219
	v_cmp_lt_i32_e32 vcc, v22, v21
	s_nop 1
	v_cndmask_b32_e32 v22, v219, v22, vcc
	v_lshlrev_b32_e32 v22, 2, v22
	ds_bpermute_b32 v22, v22, v9
	s_waitcnt lgkmcnt(0)
	v_max_f32_e32 v22, v22, v22
	v_max_f32_e32 v9, v9, v22
	v_xor_b32_e32 v22, 8, v219
	v_cmp_lt_i32_e32 vcc, v22, v21
	s_nop 1
	v_cndmask_b32_e32 v22, v219, v22, vcc
	v_lshlrev_b32_e32 v22, 2, v22
	ds_bpermute_b32 v22, v22, v9
	s_waitcnt lgkmcnt(0)
	v_max_f32_e32 v22, v22, v22
	v_max_f32_e32 v9, v9, v22
	v_xor_b32_e32 v22, 4, v219
	v_cmp_lt_i32_e32 vcc, v22, v21
	s_nop 1
	v_cndmask_b32_e32 v22, v219, v22, vcc
	v_lshlrev_b32_e32 v22, 2, v22
	ds_bpermute_b32 v22, v22, v9
	s_waitcnt lgkmcnt(0)
	v_max_f32_e32 v22, v22, v22
	v_max_f32_e32 v9, v9, v22
	v_xor_b32_e32 v22, 2, v219
	v_cmp_lt_i32_e32 vcc, v22, v21
	s_nop 1
	v_cndmask_b32_e32 v22, v219, v22, vcc
	v_lshlrev_b32_e32 v22, 2, v22
	ds_bpermute_b32 v22, v22, v9
	s_waitcnt lgkmcnt(0)
	v_max_f32_e32 v22, v22, v22
	v_max_f32_e32 v9, v9, v22
	v_xor_b32_e32 v22, 1, v219
	v_cmp_lt_i32_e32 vcc, v22, v21
	s_nop 1
	v_cndmask_b32_e32 v21, v219, v22, vcc
	v_lshlrev_b32_e32 v21, 2, v21
	ds_bpermute_b32 v21, v21, v9
	s_waitcnt lgkmcnt(0)
	v_max_f32_e32 v21, v21, v21
	v_max_f32_e32 v9, v9, v21
	v_div_scale_f32 v21, s[22:23], v9, v9, s69
	v_rcp_f32_e32 v22, v21
	v_cmp_lt_f32_e64 s[0:1], 0, v9
	v_fma_f32 v23, -v21, v22, 1.0
	v_fmac_f32_e32 v22, v23, v22
	v_div_scale_f32 v23, vcc, s69, v9, s69
	v_mul_f32_e32 v24, v23, v22
	v_fma_f32 v25, -v21, v24, v23
	v_fmac_f32_e32 v24, v25, v22
	v_fma_f32 v21, -v21, v24, v23
	v_div_fmas_f32 v21, v21, v22, v24
	v_div_fixup_f32 v21, v21, v9, s69
	v_cndmask_b32_e64 v21, 0, v21, s[0:1]
	v_mul_f32_e32 v12, v21, v12
	v_mul_f32_e32 v8, v21, v8
	v_rndne_f32_e32 v12, v12
	v_rndne_f32_e32 v8, v8
	v_cvt_i32_f32_e32 v12, v12
	v_cvt_i32_f32_e32 v8, v8
	v_mul_f32_e32 v14, v21, v14
	v_mul_f32_e32 v15, v21, v15
	v_rndne_f32_e32 v14, v14
	v_rndne_f32_e32 v15, v15
	v_cvt_i32_f32_e32 v14, v14
	v_cvt_i32_f32_e32 v15, v15
	v_mul_f32_e32 v17, v21, v17
	v_mul_f32_e32 v10, v21, v10
	v_rndne_f32_e32 v17, v17
	v_rndne_f32_e32 v10, v10
	v_add_u32_e32 v22, 8, v12
	v_add_u32_e32 v23, 8, v8
	v_cvt_i32_f32_e32 v17, v17
	v_cvt_i32_f32_e32 v10, v10
	v_mul_f32_e32 v11, v21, v11
	v_lshrrev_b32_e32 v22, 4, v22
	v_and_b32_e32 v23, 0xf0, v23
	v_mul_f32_e32 v19, v21, v19
	v_rndne_f32_e32 v11, v11
	v_and_or_b32 v22, v22, 15, v23
	v_lshl_add_u32 v23, v14, 4, v222
	v_lshl_add_u32 v24, v15, 8, v223
	v_rndne_f32_e32 v19, v19
	v_cvt_i32_f32_e32 v11, v11
	v_and_b32_e32 v23, 0xf00, v23
	v_and_b32_e32 v24, 0xf000, v24
	v_cvt_i32_f32_e32 v19, v19
	v_or3_b32 v22, v22, v23, v24
	v_lshl_add_u32 v23, v17, 12, v224
	v_lshl_add_u32 v24, v10, 16, v225
	v_and_b32_e32 v12, 15, v12
	v_lshlrev_b32_e32 v8, 4, v8
	v_lshlrev_b32_e32 v14, 8, v14
	v_and_b32_e32 v23, 0xf0000, v23
	v_and_b32_e32 v24, 0xf00000, v24
	v_and_b32_e32 v8, 0xf0, v8
	v_and_b32_e32 v14, 0xf00, v14
	v_lshlrev_b32_e32 v15, 12, v15
	v_lshlrev_b32_e32 v17, 16, v17
	v_or3_b32 v22, v22, v23, v24
	v_lshl_add_u32 v24, v11, 24, v227
	v_lshl_or_b32 v11, v11, 28, v12
	v_and_b32_e32 v15, 0xf000, v15
	v_and_b32_e32 v17, 0xf0000, v17
	v_lshlrev_b32_e32 v10, 20, v10
	v_lshl_add_u32 v23, v19, 20, v226
	v_lshlrev_b32_e32 v19, 24, v19
	v_or3_b32 v8, v11, v8, v14
	v_and_b32_e32 v10, 0xf00000, v10
	v_and_b32_e32 v19, 0xf000000, v19
	v_or3_b32 v8, v8, v15, v17
	v_or3_b32 v75, v8, v10, v19
	v_mul_f32_e32 v8, v21, v13
	v_mul_f32_e32 v4, v21, v4
	v_rndne_f32_e32 v8, v8
	v_rndne_f32_e32 v4, v4
	v_cvt_i32_f32_e32 v8, v8
	v_cvt_i32_f32_e32 v4, v4
	v_mul_f32_e32 v5, v21, v5
	v_rndne_f32_e32 v5, v5
	v_add_u32_e32 v10, 8, v8
	v_add_u32_e32 v11, 8, v4
	v_lshrrev_b32_e32 v10, 4, v10
	v_and_b32_e32 v11, 0xf0, v11
	v_and_or_b32 v10, v10, 15, v11
	v_mul_f32_e32 v11, v21, v16
	v_rndne_f32_e32 v11, v11
	v_cvt_i32_f32_e32 v11, v11
	v_cvt_i32_f32_e32 v5, v5
	v_mul_f32_e32 v6, v21, v6
	v_rndne_f32_e32 v6, v6
	v_lshl_add_u32 v12, v11, 4, v222
	v_lshl_add_u32 v13, v5, 8, v223
	v_and_b32_e32 v12, 0xf00, v12
	v_and_b32_e32 v13, 0xf000, v13
	v_or3_b32 v10, v10, v12, v13
	v_mul_f32_e32 v12, v21, v18
	v_rndne_f32_e32 v12, v12
	v_cvt_i32_f32_e32 v12, v12
	v_cvt_i32_f32_e32 v6, v6
	v_mul_f32_e32 v7, v21, v7
	v_rndne_f32_e32 v7, v7
	v_lshl_add_u32 v13, v12, 12, v224
	v_lshl_add_u32 v14, v6, 16, v225
	v_and_b32_e32 v13, 0xf0000, v13
	v_and_b32_e32 v14, 0xf00000, v14
	v_or3_b32 v10, v10, v13, v14
	v_mul_f32_e32 v13, v21, v20
	v_rndne_f32_e32 v13, v13
	v_cvt_i32_f32_e32 v7, v7
	v_cvt_i32_f32_e32 v13, v13
	v_and_b32_e32 v8, 15, v8
	v_lshlrev_b32_e32 v4, 4, v4
	v_lshlrev_b32_e32 v11, 8, v11
	v_and_b32_e32 v4, 0xf0, v4
	v_and_b32_e32 v11, 0xf00, v11
	v_lshlrev_b32_e32 v5, 12, v5
	v_lshlrev_b32_e32 v12, 16, v12
	v_lshl_add_u32 v15, v7, 24, v227
	v_lshl_or_b32 v7, v7, 28, v8
	v_and_b32_e32 v5, 0xf000, v5
	v_and_b32_e32 v12, 0xf0000, v12
	v_lshlrev_b32_e32 v6, 20, v6
	v_lshl_add_u32 v14, v13, 20, v226
	v_lshlrev_b32_e32 v13, 24, v13
	v_or3_b32 v4, v7, v4, v11
	v_and_b32_e32 v6, 0xf00000, v6
	v_and_b32_e32 v13, 0xf000000, v13
	v_or3_b32 v4, v4, v5, v12
	v_or3_b32 v108, v4, v6, v13
	v_lshlrev_b64 v[6:7], 9, v[2:3]
	v_and_b32_e32 v14, 0xf000000, v14
	v_and_b32_e32 v15, 0xf0000000, v15
	v_lshl_add_u64 v[4:5], v[62:63], 0, v[6:7]
	v_or3_b32 v77, v10, v14, v15
	s_waitcnt vmcnt(7)
	v_mov_b32_e32 v20, v112
	s_waitcnt vmcnt(6)
	v_mov_b32_e32 v18, v113
	s_waitcnt vmcnt(5)
	v_mov_b32_e32 v16, v114
	s_waitcnt vmcnt(4)
	v_mov_b32_e32 v14, v115
	s_waitcnt vmcnt(3)
	v_mov_b32_e32 v12, v116
	s_waitcnt vmcnt(2)
	v_mov_b32_e32 v10, v117
	s_waitcnt vmcnt(1)
	v_mov_b32_e32 v8, v118
	s_nop 0
	s_waitcnt vmcnt(0)
	v_mov_b32_e32 v4, v119
	v_and_b32_e32 v23, 0xf000000, v23
	v_and_b32_e32 v24, 0xf0000000, v24
	v_or3_b32 v73, v22, v23, v24
	v_mul_f32_e32 v3, 0x3c09ae41, v9
	v_lshl_add_u64 v[6:7], v[64:65], 0, v[6:7]
	v_readlane_b32 s0, v20, 0
	s_lshl_b32 s0, s0, 9
	s_nop 3
	buffer_load_dwordx2 v[100:101], v192, s[52:55], s0 offen
	v_readlane_b32 s0, v20, 1
	s_lshl_b32 s0, s0, 9
	s_nop 3
	buffer_load_dwordx2 v[102:103], v192, s[52:55], s0 offen
	v_readlane_b32 s0, v20, 2
	s_lshl_b32 s0, s0, 9
	s_nop 3
	buffer_load_dwordx2 v[98:99], v192, s[52:55], s0 offen
	v_readlane_b32 s0, v20, 3
	s_lshl_b32 s0, s0, 9
	s_nop 3
	buffer_load_dwordx2 v[104:105], v192, s[52:55], s0 offen
	v_readlane_b32 s0, v20, 4
	s_lshl_b32 s0, s0, 9
	s_nop 3
	buffer_load_dwordx2 v[94:95], v192, s[52:55], s0 offen
	v_readlane_b32 s0, v20, 5
	s_lshl_b32 s0, s0, 9
	s_nop 3
	buffer_load_dwordx2 v[86:87], v192, s[52:55], s0 offen
	v_readlane_b32 s0, v20, 6
	s_lshl_b32 s0, s0, 9
	s_nop 3
	buffer_load_dwordx2 v[84:85], v192, s[52:55], s0 offen
	v_readlane_b32 s0, v20, 7
	s_lshl_b32 s0, s0, 9
	s_nop 3
	buffer_load_dwordx2 v[90:91], v192, s[52:55], s0 offen
	v_readlane_b32 s0, v20, 8
	s_lshl_b32 s0, s0, 9
	s_nop 3
	buffer_load_dwordx2 v[78:79], v192, s[52:55], s0 offen
	v_readlane_b32 s0, v20, 9
	s_lshl_b32 s0, s0, 9
	s_nop 3
	buffer_load_dwordx2 v[50:51], v192, s[52:55], s0 offen
	v_readlane_b32 s0, v20, 10
	s_lshl_b32 s0, s0, 9
	s_nop 3
	buffer_load_dwordx2 v[48:49], v192, s[52:55], s0 offen
	v_readlane_b32 s0, v20, 11
	s_lshl_b32 s0, s0, 9
	s_nop 3
	buffer_load_dwordx2 v[54:55], v192, s[52:55], s0 offen
	v_readlane_b32 s0, v20, 12
	s_lshl_b32 s0, s0, 9
	s_nop 3
	buffer_load_dwordx2 v[42:43], v192, s[52:55], s0 offen
	v_readlane_b32 s0, v20, 13
	s_lshl_b32 s0, s0, 9
	s_nop 3
	buffer_load_dwordx2 v[34:35], v192, s[52:55], s0 offen
	v_readlane_b32 s0, v20, 14
	s_lshl_b32 s0, s0, 9
	s_nop 3
	buffer_load_dwordx2 v[32:33], v192, s[52:55], s0 offen
	v_readlane_b32 s0, v20, 15
	s_lshl_b32 s0, s0, 9
	s_nop 3
	buffer_load_dwordx2 v[38:39], v192, s[52:55], s0 offen
	v_lshlrev_b32_e32 v120, 2, v20
	v_lshlrev_b32_e32 v121, 2, v18
	v_lshlrev_b32_e32 v122, 2, v16
	v_lshlrev_b32_e32 v123, 2, v14
	v_lshlrev_b32_e32 v124, 2, v12
	v_lshlrev_b32_e32 v125, 2, v10
	v_lshlrev_b32_e32 v126, 2, v8
	v_lshlrev_b32_e32 v127, 2, v4
	global_load_dword v128, v120, s[8:9]
	global_load_dword v136, v120, s[10:11]
	global_load_dword v144, v[6:7], off
	global_load_dword v129, v121, s[8:9]
	global_load_dword v137, v121, s[10:11]
	global_load_dword v145, v[6:7], off offset:64
	global_load_dword v130, v122, s[8:9]
	global_load_dword v138, v122, s[10:11]
	global_load_dword v146, v[6:7], off offset:128
	global_load_dword v131, v123, s[8:9]
	global_load_dword v139, v123, s[10:11]
	global_load_dword v147, v[6:7], off offset:192
	global_load_dword v132, v124, s[8:9]
	global_load_dword v140, v124, s[10:11]
	global_load_dword v148, v[6:7], off offset:256
	global_load_dword v133, v125, s[8:9]
	global_load_dword v141, v125, s[10:11]
	global_load_dword v149, v[6:7], off offset:320
	global_load_dword v134, v126, s[8:9]
	global_load_dword v142, v126, s[10:11]
	global_load_dword v150, v[6:7], off offset:384
	global_load_dword v135, v127, s[8:9]
	global_load_dword v143, v127, s[10:11]
	global_load_dword v151, v[6:7], off offset:448
	s_nop 3
	s_waitcnt vmcnt(39)
	v_dot8_i32_i4 v5, v100, v73, 0
	s_nop 1
	v_dot8_i32_i4 v9, v100, v75, 0
	v_dot8_i32_i4 v5, v101, v77, v5
	v_dot8_i32_i4 v9, v101, v108, v9
	s_waitcnt vmcnt(38)
	v_dot8_i32_i4 v11, v102, v75, 0
	s_nop 0
	v_lshl_add_u32 v5, v5, 4, v9
	v_dot8_i32_i4 v9, v102, v73, 0
	v_dot8_i32_i4 v9, v103, v77, v9
	v_dot8_i32_i4 v11, v103, v108, v11
	v_cvt_f32_i32_e32 v5, v5
	s_waitcnt vmcnt(37)
	v_dot8_i32_i4 v13, v98, v75, 0
	v_lshl_add_u32 v9, v9, 4, v11
	v_dot8_i32_i4 v11, v98, v73, 0
	v_dot8_i32_i4 v11, v99, v77, v11
	v_dot8_i32_i4 v13, v99, v108, v13
	s_waitcnt vmcnt(36)
	v_dot8_i32_i4 v15, v104, v75, 0
	v_dot8_i32_i4 v15, v105, v108, v15
	v_cvt_f32_i32_e32 v9, v9
	v_lshl_add_u32 v11, v11, 4, v13
	v_dot8_i32_i4 v13, v104, v73, 0
	v_dot8_i32_i4 v13, v105, v77, v13
	s_nop 1
	s_nop 0
	v_lshl_add_u32 v13, v13, 4, v15
	v_cvt_f32_i32_e32 v11, v11
	s_nop 0
	v_cvt_f32_i32_e32 v13, v13
	s_waitcnt vmcnt(35)
	v_dot8_i32_i4 v15, v94, v73, 0
	s_nop 1
	v_dot8_i32_i4 v17, v94, v75, 0
	v_dot8_i32_i4 v15, v95, v77, v15
	v_dot8_i32_i4 v17, v95, v108, v17
	s_waitcnt vmcnt(34)
	v_dot8_i32_i4 v19, v86, v75, 0
	s_nop 0
	v_lshl_add_u32 v15, v15, 4, v17
	v_dot8_i32_i4 v17, v86, v73, 0
	v_dot8_i32_i4 v17, v87, v77, v17
	v_dot8_i32_i4 v19, v87, v108, v19
	s_waitcnt vmcnt(33)
	v_dot8_i32_i4 v21, v84, v75, 0
	v_dot8_i32_i4 v21, v85, v108, v21
	v_cvt_f32_i32_e32 v15, v15
	v_lshl_add_u32 v17, v17, 4, v19
	v_dot8_i32_i4 v19, v84, v73, 0
	v_dot8_i32_i4 v19, v85, v77, v19
	s_nop 1
	s_nop 0
	v_lshl_add_u32 v19, v19, 4, v21
	s_waitcnt vmcnt(32)
	v_dot8_i32_i4 v21, v90, v73, 0
	v_dot8_i32_i4 v84, v90, v75, 0
	v_dot8_i32_i4 v21, v91, v77, v21
	v_dot8_i32_i4 v84, v91, v108, v84
	v_readlane_b32 s0, v18, 0
	s_lshl_b32 s0, s0, 9
	s_nop 0
	v_lshl_add_u32 v21, v21, 4, v84
	s_waitcnt vmcnt(31)
	v_dot8_i32_i4 v84, v78, v73, 0
	v_dot8_i32_i4 v85, v78, v75, 0
	buffer_load_dwordx2 v[96:97], v192, s[52:55], s0 offen
	v_readlane_b32 s0, v18, 1
	s_lshl_b32 s0, s0, 9
	v_dot8_i32_i4 v84, v79, v77, v84
	v_dot8_i32_i4 v85, v79, v108, v85
	v_cvt_f32_i32_e32 v17, v17
	buffer_load_dwordx2 v[88:89], v192, s[52:55], s0 offen
	v_readlane_b32 s0, v18, 2
	s_lshl_b32 s0, s0, 9
	v_lshl_add_u32 v78, v84, 4, v85
	v_cvt_f32_i32_e32 v19, v19
	v_cvt_f32_i32_e32 v21, v21
	buffer_load_dwordx2 v[82:83], v192, s[52:55], s0 offen
	v_readlane_b32 s0, v18, 3
	s_lshl_b32 s0, s0, 9
	v_cvt_f32_i32_e32 v78, v78
	s_waitcnt vmcnt(33)
	v_dot8_i32_i4 v79, v50, v73, 0
	s_nop 0
	buffer_load_dwordx2 v[92:93], v192, s[52:55], s0 offen
	v_readlane_b32 s0, v18, 4
	s_lshl_b32 s0, s0, 9
	v_dot8_i32_i4 v84, v50, v75, 0
	v_dot8_i32_i4 v79, v51, v77, v79
	v_dot8_i32_i4 v84, v51, v108, v84
	buffer_load_dwordx2 v[80:81], v192, s[52:55], s0 offen
	v_readlane_b32 s0, v18, 5
	s_lshl_b32 s0, s0, 9
	v_lshl_add_u32 v50, v79, 4, v84
	s_waitcnt vmcnt(34)
	v_dot8_i32_i4 v51, v48, v73, 0
	v_dot8_i32_i4 v79, v48, v75, 0
	buffer_load_dwordx2 v[52:53], v192, s[52:55], s0 offen
	v_readlane_b32 s0, v18, 6
	s_lshl_b32 s0, s0, 9
	v_dot8_i32_i4 v51, v49, v77, v51
	v_dot8_i32_i4 v79, v49, v108, v79
	s_waitcnt vmcnt(34)
	v_dot8_i32_i4 v49, v54, v73, 0
	buffer_load_dwordx2 v[46:47], v192, s[52:55], s0 offen
	v_readlane_b32 s0, v18, 7
	s_lshl_b32 s0, s0, 9
	v_lshl_add_u32 v48, v51, 4, v79
	v_dot8_i32_i4 v51, v54, v75, 0
	v_dot8_i32_i4 v49, v55, v77, v49
	buffer_load_dwordx2 v[56:57], v192, s[52:55], s0 offen
	v_readlane_b32 s0, v18, 8
	s_lshl_b32 s0, s0, 9
	v_dot8_i32_i4 v51, v55, v108, v51
	s_waitcnt vmcnt(35)
	v_dot8_i32_i4 v54, v42, v75, 0
	v_dot8_i32_i4 v54, v43, v108, v54
	buffer_load_dwordx2 v[44:45], v192, s[52:55], s0 offen
	v_readlane_b32 s0, v18, 9
	s_lshl_b32 s0, s0, 9
	v_lshl_add_u32 v49, v49, 4, v51
	v_dot8_i32_i4 v51, v42, v73, 0
	v_dot8_i32_i4 v51, v43, v77, v51
	buffer_load_dwordx2 v[36:37], v192, s[52:55], s0 offen
	v_readlane_b32 s0, v18, 10
	s_lshl_b32 s0, s0, 9
	v_lshl_add_u32 v42, v51, 4, v54
	s_waitcnt vmcnt(36)
	v_dot8_i32_i4 v43, v34, v73, 0
	buffer_load_dwordx2 v[30:31], v192, s[52:55], s0 offen
	v_readlane_b32 s0, v18, 11
	s_lshl_b32 s0, s0, 9
	v_dot8_i32_i4 v51, v34, v75, 0
	v_dot8_i32_i4 v43, v35, v77, v43
	v_dot8_i32_i4 v51, v35, v108, v51
	buffer_load_dwordx2 v[40:41], v192, s[52:55], s0 offen
	v_readlane_b32 s0, v18, 12
	s_lshl_b32 s0, s0, 9
	v_lshl_add_u32 v34, v43, 4, v51
	s_waitcnt vmcnt(37)
	v_dot8_i32_i4 v35, v32, v73, 0
	v_dot8_i32_i4 v43, v32, v75, 0
	buffer_load_dwordx2 v[28:29], v192, s[52:55], s0 offen
	v_readlane_b32 s0, v18, 13
	s_lshl_b32 s0, s0, 9
	v_dot8_i32_i4 v35, v33, v77, v35
	v_dot8_i32_i4 v43, v33, v108, v43
	s_waitcnt vmcnt(37)
	v_dot8_i32_i4 v33, v38, v73, 0
	buffer_load_dwordx2 v[24:25], v192, s[52:55], s0 offen
	v_readlane_b32 s0, v18, 14
	s_lshl_b32 s0, s0, 9
	v_lshl_add_u32 v32, v35, 4, v43
	v_dot8_i32_i4 v35, v38, v75, 0
	v_dot8_i32_i4 v33, v39, v77, v33
	buffer_load_dwordx2 v[22:23], v192, s[52:55], s0 offen
	v_readlane_b32 s0, v18, 15
	s_lshl_b32 s0, s0, 9
	v_dot8_i32_i4 v35, v39, v108, v35
	v_cvt_f32_i32_e32 v50, v50
	v_cvt_f32_i32_e32 v48, v48
	v_cvt_f32_i32_e32 v49, v49
	buffer_load_dwordx2 v[26:27], v192, s[52:55], s0 offen
	v_lshl_add_u32 v33, v33, 4, v35
	v_cndmask_b32_e64 v35, v9, v5, s[40:41]
	v_cndmask_b32_e64 v5, v5, v9, s[40:41]
	v_cndmask_b32_e64 v9, v13, v11, s[40:41]
	v_cndmask_b32_e64 v11, v11, v13, s[40:41]
	ds_swizzle_b32 v11, v11 offset:swizzle(SWAP,1)
	v_cndmask_b32_e64 v13, v15, v17, s[40:41]
	ds_swizzle_b32 v13, v13 offset:swizzle(SWAP,1)
	v_cvt_f32_i32_e32 v42, v42
	v_cvt_f32_i32_e32 v34, v34
	s_waitcnt lgkmcnt(1)
	v_add_f32_e32 v9, v9, v11
	v_cndmask_b32_e64 v11, v17, v15, s[40:41]
	v_cndmask_b32_e64 v15, v19, v21, s[40:41]
	ds_swizzle_b32 v15, v15 offset:swizzle(SWAP,1)
	v_cndmask_b32_e64 v17, v78, v50, s[40:41]
	s_waitcnt lgkmcnt(1)
	v_add_f32_e32 v11, v11, v13
	v_cndmask_b32_e64 v13, v21, v19, s[40:41]
	ds_swizzle_b32 v17, v17 offset:swizzle(SWAP,1)
	v_cndmask_b32_e64 v19, v48, v49, s[40:41]
	ds_swizzle_b32 v19, v19 offset:swizzle(SWAP,1)
	v_cndmask_b32_e64 v21, v42, v34, s[40:41]
	ds_swizzle_b32 v21, v21 offset:swizzle(SWAP,1)
	v_cvt_f32_i32_e32 v32, v32
	v_cvt_f32_i32_e32 v33, v33
	s_waitcnt lgkmcnt(3)
	v_add_f32_e32 v13, v13, v15
	v_cndmask_b32_e64 v15, v50, v78, s[40:41]
	s_waitcnt lgkmcnt(2)
	v_add_f32_e32 v15, v15, v17
	v_cndmask_b32_e64 v17, v49, v48, s[40:41]
	s_waitcnt lgkmcnt(1)
	v_add_f32_e32 v17, v17, v19
	v_cndmask_b32_e64 v19, v34, v42, s[40:41]
	ds_swizzle_b32 v5, v5 offset:swizzle(SWAP,1)
	s_waitcnt lgkmcnt(1)
	v_add_f32_e32 v19, v19, v21
	v_cndmask_b32_e64 v21, v33, v32, s[40:41]
	v_cndmask_b32_e64 v32, v32, v33, s[40:41]
	ds_swizzle_b32 v32, v32 offset:swizzle(SWAP,1)
	s_waitcnt lgkmcnt(1)
	v_add_f32_e32 v5, v35, v5
	s_waitcnt lgkmcnt(0)
	v_add_f32_e32 v21, v21, v32
	v_cndmask_b32_e64 v32, v9, v5, s[42:43]
	v_cndmask_b32_e64 v5, v5, v9, s[42:43]
	v_cndmask_b32_e64 v9, v13, v11, s[42:43]
	v_cndmask_b32_e64 v11, v11, v13, s[42:43]
	ds_swizzle_b32 v11, v11 offset:swizzle(SWAP,2)
	v_cndmask_b32_e64 v13, v15, v17, s[42:43]
	ds_swizzle_b32 v13, v13 offset:swizzle(SWAP,2)
	ds_swizzle_b32 v5, v5 offset:swizzle(SWAP,2)
	s_waitcnt lgkmcnt(2)
	v_add_f32_e32 v9, v9, v11
	v_cndmask_b32_e64 v11, v17, v15, s[42:43]
	v_cndmask_b32_e64 v15, v19, v21, s[42:43]
	ds_swizzle_b32 v15, v15 offset:swizzle(SWAP,2)
	s_waitcnt lgkmcnt(2)
	v_add_f32_e32 v11, v11, v13
	v_cndmask_b32_e64 v13, v21, v19, s[42:43]
	s_waitcnt lgkmcnt(1)
	v_add_f32_e32 v5, v32, v5
	s_waitcnt lgkmcnt(0)
	v_add_f32_e32 v13, v13, v15
	v_cndmask_b32_e64 v15, v9, v5, s[44:45]
	v_cndmask_b32_e64 v5, v5, v9, s[44:45]
	v_cndmask_b32_e64 v9, v13, v11, s[44:45]
	v_cndmask_b32_e64 v11, v11, v13, s[44:45]
	ds_swizzle_b32 v5, v5 offset:swizzle(SWAP,4)
	ds_swizzle_b32 v11, v11 offset:swizzle(SWAP,4)
	s_waitcnt lgkmcnt(1)
	v_add_f32_e32 v5, v15, v5
	s_waitcnt lgkmcnt(0)
	v_add_f32_e32 v9, v9, v11
	v_cndmask_b32_e64 v11, v9, v5, s[46:47]
	v_cndmask_b32_e64 v5, v5, v9, s[46:47]
	ds_swizzle_b32 v5, v5 offset:swizzle(SWAP,8)
	s_waitcnt lgkmcnt(0)
	v_add_f32_e32 v5, v11, v5
	ds_swizzle_b32 v9, v5 offset:swizzle(SWAP,16)
	s_waitcnt lgkmcnt(0)
	v_add_f32_e32 v5, v5, v9
	ds_bpermute_b32 v9, v0, v5
	s_and_saveexec_b64 s[0:1], s[48:49]
	s_cbranch_execz .LBB0_541
	v_ashrrev_i32_e32 v21, 31, v20
	v_lshlrev_b64 v[20:21], 2, v[20:21]
	v_lshl_add_u64 v[32:33], s[8:9], 0, v[20:21]
	s_waitcnt vmcnt(39)
	v_mov_b32_e32 v11, v128
	v_lshl_add_u64 v[20:21], s[10:11], 0, v[20:21]
	s_waitcnt vmcnt(37)
	v_mov_b32_e32 v13, v144
	v_mov_b32_e32 v15, v136
	s_waitcnt lgkmcnt(0)
	v_add_f32_e32 v5, v5, v9
	v_mul_f32_e32 v5, v5, v11
	v_mul_f32_e32 v5, v3, v5
	v_mul_f32_e32 v11, 0x3d372713, v5
	v_mul_f32_e32 v11, v5, v11
	v_mul_f32_e32 v9, 0.5, v5
	v_fmac_f32_e32 v5, v5, v11
	v_mul_f32_e32 v5, 0x3f4c422a, v5
	v_add_f32_e32 v5, v5, v5
	v_mul_f32_e32 v5, 0x3fb8aa3b, v5
	v_exp_f32_e32 v5, v5
	s_nop 0
	v_add_f32_e32 v5, 1.0, v5
	v_rcp_f32_e32 v5, v5
	s_nop 0
	v_fma_f32 v5, v5, -2.0, 1.0
	v_add_f32_e32 v5, 1.0, v5
	v_mul_f32_e32 v5, v9, v5
	v_mul_f32_e32 v5, v13, v5
	v_mul_f32_e32 v5, v15, v5
	ds_write_b32 v109, v5
.LBB0_541:
	s_or_b64 exec, exec, s[0:1]
	v_readlane_b32 s0, v16, 0
	s_lshl_b32 s0, s0, 9
	s_waitcnt lgkmcnt(0)
	s_waitcnt vmcnt(15)
	v_dot8_i32_i4 v5, v96, v73, 0
	v_dot8_i32_i4 v9, v96, v75, 0
	buffer_load_dwordx2 v[102:103], v192, s[52:55], s0 offen
	v_readlane_b32 s0, v16, 1
	s_lshl_b32 s0, s0, 9
	v_dot8_i32_i4 v5, v97, v77, v5
	v_dot8_i32_i4 v9, v97, v108, v9
	s_waitcnt vmcnt(15)
	v_dot8_i32_i4 v11, v88, v75, 0
	buffer_load_dwordx2 v[98:99], v192, s[52:55], s0 offen
	v_readlane_b32 s0, v16, 2
	s_lshl_b32 s0, s0, 9
	v_lshl_add_u32 v5, v5, 4, v9
	v_dot8_i32_i4 v9, v88, v73, 0
	v_dot8_i32_i4 v9, v89, v77, v9
	buffer_load_dwordx2 v[94:95], v192, s[52:55], s0 offen
	v_readlane_b32 s0, v16, 3
	s_lshl_b32 s0, s0, 9
	v_dot8_i32_i4 v11, v89, v108, v11
	s_waitcnt vmcnt(16)
	v_dot8_i32_i4 v13, v82, v75, 0
	v_dot8_i32_i4 v13, v83, v108, v13
	buffer_load_dwordx2 v[100:101], v192, s[52:55], s0 offen
	v_readlane_b32 s0, v16, 4
	s_lshl_b32 s0, s0, 9
	v_lshl_add_u32 v9, v9, 4, v11
	v_dot8_i32_i4 v11, v82, v73, 0
	v_dot8_i32_i4 v11, v83, v77, v11
	buffer_load_dwordx2 v[90:91], v192, s[52:55], s0 offen
	v_readlane_b32 s0, v16, 5
	s_lshl_b32 s0, s0, 9
	v_lshl_add_u32 v11, v11, 4, v13
	s_waitcnt vmcnt(17)
	v_dot8_i32_i4 v13, v92, v73, 0
	buffer_load_dwordx2 v[84:85], v192, s[52:55], s0 offen
	v_readlane_b32 s0, v16, 6
	s_lshl_b32 s0, s0, 9
	v_dot8_i32_i4 v15, v92, v75, 0
	v_dot8_i32_i4 v13, v93, v77, v13
	v_dot8_i32_i4 v15, v93, v108, v15
	buffer_load_dwordx2 v[78:79], v192, s[52:55], s0 offen
	v_readlane_b32 s0, v16, 7
	s_lshl_b32 s0, s0, 9
	v_lshl_add_u32 v13, v13, 4, v15
	s_waitcnt vmcnt(18)
	v_dot8_i32_i4 v15, v80, v73, 0
	v_dot8_i32_i4 v17, v80, v75, 0
	buffer_load_dwordx2 v[86:87], v192, s[52:55], s0 offen
	v_readlane_b32 s0, v16, 8
	s_lshl_b32 s0, s0, 9
	v_dot8_i32_i4 v15, v81, v77, v15
	v_dot8_i32_i4 v17, v81, v108, v17
	s_waitcnt vmcnt(18)
	v_dot8_i32_i4 v19, v52, v75, 0
	buffer_load_dwordx2 v[54:55], v192, s[52:55], s0 offen
	v_readlane_b32 s0, v16, 9
	s_lshl_b32 s0, s0, 9
	v_lshl_add_u32 v15, v15, 4, v17
	v_dot8_i32_i4 v17, v52, v73, 0
	v_dot8_i32_i4 v17, v53, v77, v17
	buffer_load_dwordx2 v[48:49], v192, s[52:55], s0 offen
	v_readlane_b32 s0, v16, 10
	s_lshl_b32 s0, s0, 9
	v_dot8_i32_i4 v19, v53, v108, v19
	s_waitcnt vmcnt(19)
	v_dot8_i32_i4 v52, v46, v75, 0
	v_dot8_i32_i4 v52, v47, v108, v52
	buffer_load_dwordx2 v[42:43], v192, s[52:55], s0 offen
	v_readlane_b32 s0, v16, 11
	s_lshl_b32 s0, s0, 9
	v_lshl_add_u32 v17, v17, 4, v19
	v_dot8_i32_i4 v19, v46, v73, 0
	v_dot8_i32_i4 v19, v47, v77, v19
	buffer_load_dwordx2 v[50:51], v192, s[52:55], s0 offen
	v_readlane_b32 s0, v16, 12
	s_lshl_b32 s0, s0, 9
	s_waitcnt vmcnt(20)
	v_dot8_i32_i4 v46, v56, v73, 0
	v_dot8_i32_i4 v47, v56, v75, 0
	buffer_load_dwordx2 v[38:39], v192, s[52:55], s0 offen
	v_readlane_b32 s0, v16, 13
	s_lshl_b32 s0, s0, 9
	v_dot8_i32_i4 v46, v57, v77, v46
	v_dot8_i32_i4 v47, v57, v108, v47
	v_lshl_add_u32 v19, v19, 4, v52
	buffer_load_dwordx2 v[32:33], v192, s[52:55], s0 offen
	v_readlane_b32 s0, v16, 14
	s_lshl_b32 s0, s0, 9
	v_lshl_add_u32 v46, v46, 4, v47
	s_waitcnt vmcnt(21)
	v_dot8_i32_i4 v47, v44, v73, 0
	v_dot8_i32_i4 v52, v44, v75, 0
	buffer_load_dwordx2 v[20:21], v192, s[52:55], s0 offen
	v_readlane_b32 s0, v16, 15
	s_lshl_b32 s0, s0, 9
	v_dot8_i32_i4 v47, v45, v77, v47
	v_dot8_i32_i4 v52, v45, v108, v52
	s_waitcnt vmcnt(21)
	v_dot8_i32_i4 v45, v36, v73, 0
	buffer_load_dwordx2 v[34:35], v192, s[52:55], s0 offen
	v_lshl_add_u32 v44, v47, 4, v52
	v_dot8_i32_i4 v47, v36, v75, 0
	v_dot8_i32_i4 v45, v37, v77, v45
	v_dot8_i32_i4 v47, v37, v108, v47
	s_waitcnt vmcnt(21)
	v_dot8_i32_i4 v37, v30, v73, 0
	v_dot8_i32_i4 v37, v31, v77, v37
	v_lshl_add_u32 v36, v45, 4, v47
	v_dot8_i32_i4 v45, v30, v75, 0
	v_dot8_i32_i4 v45, v31, v108, v45
	s_waitcnt vmcnt(20)
	v_dot8_i32_i4 v31, v40, v73, 0
	v_dot8_i32_i4 v31, v41, v77, v31
	v_lshl_add_u32 v30, v37, 4, v45
	v_dot8_i32_i4 v37, v40, v75, 0
	v_dot8_i32_i4 v37, v41, v108, v37
	s_waitcnt vmcnt(19)
	v_dot8_i32_i4 v40, v28, v75, 0
	v_dot8_i32_i4 v40, v29, v108, v40
	v_lshl_add_u32 v31, v31, 4, v37
	v_dot8_i32_i4 v37, v28, v73, 0
	v_dot8_i32_i4 v37, v29, v77, v37
	s_waitcnt vmcnt(18)
	v_dot8_i32_i4 v29, v24, v73, 0
	v_dot8_i32_i4 v29, v25, v77, v29
	v_lshl_add_u32 v28, v37, 4, v40
	v_dot8_i32_i4 v37, v24, v75, 0
	v_dot8_i32_i4 v37, v25, v108, v37
	s_waitcnt vmcnt(17)
	v_dot8_i32_i4 v25, v22, v73, 0
	v_cvt_f32_i32_e32 v5, v5
	v_lshl_add_u32 v24, v29, 4, v37
	v_dot8_i32_i4 v29, v22, v75, 0
	v_cvt_f32_i32_e32 v9, v9
	v_cvt_f32_i32_e32 v11, v11
	v_cvt_f32_i32_e32 v13, v13
	v_dot8_i32_i4 v25, v23, v77, v25
	v_dot8_i32_i4 v29, v23, v108, v29
	v_cvt_f32_i32_e32 v15, v15
	v_cvt_f32_i32_e32 v17, v17
	s_nop 0
	v_lshl_add_u32 v22, v25, 4, v29
	s_waitcnt vmcnt(16)
	v_dot8_i32_i4 v23, v26, v73, 0
	v_dot8_i32_i4 v25, v26, v75, 0
	v_dot8_i32_i4 v23, v27, v77, v23
	v_dot8_i32_i4 v25, v27, v108, v25
	v_cvt_f32_i32_e32 v19, v19
	v_cvt_f32_i32_e32 v46, v46
	v_cvt_f32_i32_e32 v44, v44
	v_lshl_add_u32 v23, v23, 4, v25
	v_cndmask_b32_e64 v25, v9, v5, s[40:41]
	v_cndmask_b32_e64 v5, v5, v9, s[40:41]
	v_cndmask_b32_e64 v9, v13, v11, s[40:41]
	v_cndmask_b32_e64 v11, v11, v13, s[40:41]
	ds_swizzle_b32 v11, v11 offset:swizzle(SWAP,1)
	v_cndmask_b32_e64 v13, v15, v17, s[40:41]
	v_cvt_f32_i32_e32 v36, v36
	ds_swizzle_b32 v13, v13 offset:swizzle(SWAP,1)
	v_cvt_f32_i32_e32 v30, v30
	v_cvt_f32_i32_e32 v31, v31
	s_waitcnt lgkmcnt(1)
	v_add_f32_e32 v9, v9, v11
	v_cndmask_b32_e64 v11, v17, v15, s[40:41]
	v_cndmask_b32_e64 v15, v19, v46, s[40:41]
	ds_swizzle_b32 v15, v15 offset:swizzle(SWAP,1)
	v_cndmask_b32_e64 v17, v44, v36, s[40:41]
	s_waitcnt lgkmcnt(1)
	v_add_f32_e32 v11, v11, v13
	v_cndmask_b32_e64 v13, v46, v19, s[40:41]
	ds_swizzle_b32 v17, v17 offset:swizzle(SWAP,1)
	v_cndmask_b32_e64 v19, v30, v31, s[40:41]
	ds_swizzle_b32 v19, v19 offset:swizzle(SWAP,1)
	v_cvt_f32_i32_e32 v28, v28
	v_cvt_f32_i32_e32 v24, v24
	s_waitcnt lgkmcnt(2)
	v_add_f32_e32 v13, v13, v15
	v_cndmask_b32_e64 v15, v36, v44, s[40:41]
	s_waitcnt lgkmcnt(1)
	v_add_f32_e32 v15, v15, v17
	v_cndmask_b32_e64 v17, v31, v30, s[40:41]
	s_waitcnt lgkmcnt(0)
	v_add_f32_e32 v17, v17, v19
	v_cndmask_b32_e64 v19, v24, v28, s[40:41]
	v_cndmask_b32_e64 v24, v28, v24, s[40:41]
	ds_swizzle_b32 v5, v5 offset:swizzle(SWAP,1)
	ds_swizzle_b32 v24, v24 offset:swizzle(SWAP,1)
	v_cvt_f32_i32_e32 v22, v22
	v_cvt_f32_i32_e32 v23, v23
	s_waitcnt lgkmcnt(1)
	v_add_f32_e32 v5, v25, v5
	s_waitcnt lgkmcnt(0)
	v_add_f32_e32 v19, v19, v24
	v_cndmask_b32_e64 v24, v23, v22, s[40:41]
	v_cndmask_b32_e64 v22, v22, v23, s[40:41]
	ds_swizzle_b32 v22, v22 offset:swizzle(SWAP,1)
	v_cndmask_b32_e64 v23, v9, v5, s[42:43]
	v_cndmask_b32_e64 v5, v5, v9, s[42:43]
	v_cndmask_b32_e64 v9, v13, v11, s[42:43]
	v_cndmask_b32_e64 v11, v11, v13, s[42:43]
	ds_swizzle_b32 v11, v11 offset:swizzle(SWAP,2)
	s_waitcnt lgkmcnt(1)
	v_add_f32_e32 v22, v24, v22
	v_cndmask_b32_e64 v13, v15, v17, s[42:43]
	ds_swizzle_b32 v13, v13 offset:swizzle(SWAP,2)
	ds_swizzle_b32 v5, v5 offset:swizzle(SWAP,2)
	s_waitcnt lgkmcnt(2)
	v_add_f32_e32 v9, v9, v11
	v_cndmask_b32_e64 v11, v17, v15, s[42:43]
	v_cndmask_b32_e64 v15, v19, v22, s[42:43]
	ds_swizzle_b32 v15, v15 offset:swizzle(SWAP,2)
	s_waitcnt lgkmcnt(2)
	v_add_f32_e32 v11, v11, v13
	v_cndmask_b32_e64 v13, v22, v19, s[42:43]
	s_waitcnt lgkmcnt(1)
	v_add_f32_e32 v5, v23, v5
	s_waitcnt lgkmcnt(0)
	v_add_f32_e32 v13, v13, v15
	v_cndmask_b32_e64 v15, v9, v5, s[44:45]
	v_cndmask_b32_e64 v5, v5, v9, s[44:45]
	v_cndmask_b32_e64 v9, v13, v11, s[44:45]
	v_cndmask_b32_e64 v11, v11, v13, s[44:45]
	ds_swizzle_b32 v5, v5 offset:swizzle(SWAP,4)
	ds_swizzle_b32 v11, v11 offset:swizzle(SWAP,4)
	s_waitcnt lgkmcnt(1)
	v_add_f32_e32 v5, v15, v5
	s_waitcnt lgkmcnt(0)
	v_add_f32_e32 v9, v9, v11
	v_cndmask_b32_e64 v11, v9, v5, s[46:47]
	v_cndmask_b32_e64 v5, v5, v9, s[46:47]
	ds_swizzle_b32 v5, v5 offset:swizzle(SWAP,8)
	s_waitcnt lgkmcnt(0)
	v_add_f32_e32 v5, v11, v5
	ds_swizzle_b32 v9, v5 offset:swizzle(SWAP,16)
	s_waitcnt lgkmcnt(0)
	v_add_f32_e32 v5, v5, v9
	ds_bpermute_b32 v9, v0, v5
	s_and_saveexec_b64 s[0:1], s[48:49]
	s_cbranch_execz .LBB0_543
	v_ashrrev_i32_e32 v19, 31, v18
	v_lshlrev_b64 v[18:19], 2, v[18:19]
	v_lshl_add_u64 v[22:23], s[8:9], 0, v[18:19]
	v_mov_b32_e32 v11, v129
	v_lshl_add_u64 v[18:19], s[10:11], 0, v[18:19]
	v_mov_b32_e32 v13, v145
	v_mov_b32_e32 v15, v137
	s_waitcnt lgkmcnt(0)
	v_add_f32_e32 v5, v5, v9
	v_mul_f32_e32 v5, v5, v11
	v_mul_f32_e32 v5, v3, v5
	v_mul_f32_e32 v11, 0x3d372713, v5
	v_mul_f32_e32 v11, v5, v11
	v_mul_f32_e32 v9, 0.5, v5
	v_fmac_f32_e32 v5, v5, v11
	v_mul_f32_e32 v5, 0x3f4c422a, v5
	v_add_f32_e32 v5, v5, v5
	v_mul_f32_e32 v5, 0x3fb8aa3b, v5
	v_exp_f32_e32 v5, v5
	s_nop 0
	v_add_f32_e32 v5, 1.0, v5
	v_rcp_f32_e32 v5, v5
	s_nop 0
	v_fma_f32 v5, v5, -2.0, 1.0
	v_add_f32_e32 v5, 1.0, v5
	v_mul_f32_e32 v5, v9, v5
	v_mul_f32_e32 v5, v13, v5
	v_mul_f32_e32 v5, v15, v5
	ds_write_b32 v109, v5 offset:64
.LBB0_543:
	s_or_b64 exec, exec, s[0:1]
	v_readlane_b32 s0, v14, 0
	s_lshl_b32 s0, s0, 9
	s_waitcnt lgkmcnt(0)
	s_waitcnt vmcnt(15)
	v_dot8_i32_i4 v5, v102, v73, 0
	v_dot8_i32_i4 v9, v102, v75, 0
	buffer_load_dwordx2 v[96:97], v192, s[52:55], s0 offen
	v_readlane_b32 s0, v14, 1
	s_lshl_b32 s0, s0, 9
	v_dot8_i32_i4 v5, v103, v77, v5
	v_dot8_i32_i4 v9, v103, v108, v9
	s_waitcnt vmcnt(15)
	v_dot8_i32_i4 v11, v98, v75, 0
	buffer_load_dwordx2 v[104:105], v192, s[52:55], s0 offen
	v_readlane_b32 s0, v14, 2
	s_lshl_b32 s0, s0, 9
	v_lshl_add_u32 v5, v5, 4, v9
	v_dot8_i32_i4 v9, v98, v73, 0
	v_dot8_i32_i4 v9, v99, v77, v9
	buffer_load_dwordx2 v[92:93], v192, s[52:55], s0 offen
	v_readlane_b32 s0, v14, 3
	s_lshl_b32 s0, s0, 9
	v_dot8_i32_i4 v11, v99, v108, v11
	s_waitcnt vmcnt(16)
	v_dot8_i32_i4 v13, v94, v75, 0
	v_dot8_i32_i4 v13, v95, v108, v13
	buffer_load_dwordx2 v[106:107], v192, s[52:55], s0 offen
	v_readlane_b32 s0, v14, 4
	s_lshl_b32 s0, s0, 9
	v_lshl_add_u32 v9, v9, 4, v11
	v_dot8_i32_i4 v11, v94, v73, 0
	v_dot8_i32_i4 v11, v95, v77, v11
	buffer_load_dwordx2 v[88:89], v192, s[52:55], s0 offen
	v_readlane_b32 s0, v14, 5
	s_lshl_b32 s0, s0, 9
	v_lshl_add_u32 v11, v11, 4, v13
	s_waitcnt vmcnt(17)
	v_dot8_i32_i4 v13, v100, v73, 0
	buffer_load_dwordx2 v[80:81], v192, s[52:55], s0 offen
	v_readlane_b32 s0, v14, 6
	s_lshl_b32 s0, s0, 9
	v_dot8_i32_i4 v15, v100, v75, 0
	v_dot8_i32_i4 v13, v101, v77, v13
	v_dot8_i32_i4 v15, v101, v108, v15
	buffer_load_dwordx2 v[56:57], v192, s[52:55], s0 offen
	v_readlane_b32 s0, v14, 7
	s_lshl_b32 s0, s0, 9
	v_lshl_add_u32 v13, v13, 4, v15
	s_waitcnt vmcnt(18)
	v_dot8_i32_i4 v15, v90, v73, 0
	v_dot8_i32_i4 v17, v90, v75, 0
	buffer_load_dwordx2 v[82:83], v192, s[52:55], s0 offen
	v_readlane_b32 s0, v14, 8
	s_lshl_b32 s0, s0, 9
	v_dot8_i32_i4 v15, v91, v77, v15
	v_dot8_i32_i4 v17, v91, v108, v17
	s_waitcnt vmcnt(18)
	v_dot8_i32_i4 v22, v84, v75, 0
	buffer_load_dwordx2 v[52:53], v192, s[52:55], s0 offen
	v_readlane_b32 s0, v14, 9
	s_lshl_b32 s0, s0, 9
	v_lshl_add_u32 v15, v15, 4, v17
	v_dot8_i32_i4 v17, v84, v73, 0
	v_dot8_i32_i4 v17, v85, v77, v17
	buffer_load_dwordx2 v[44:45], v192, s[52:55], s0 offen
	v_readlane_b32 s0, v14, 10
	s_lshl_b32 s0, s0, 9
	v_dot8_i32_i4 v22, v85, v108, v22
	s_waitcnt vmcnt(19)
	v_dot8_i32_i4 v23, v78, v75, 0
	v_dot8_i32_i4 v23, v79, v108, v23
	buffer_load_dwordx2 v[40:41], v192, s[52:55], s0 offen
	v_readlane_b32 s0, v14, 11
	s_lshl_b32 s0, s0, 9
	v_lshl_add_u32 v17, v17, 4, v22
	v_dot8_i32_i4 v22, v78, v73, 0
	v_dot8_i32_i4 v22, v79, v77, v22
	buffer_load_dwordx2 v[46:47], v192, s[52:55], s0 offen
	v_readlane_b32 s0, v14, 12
	s_lshl_b32 s0, s0, 9
	v_lshl_add_u32 v22, v22, 4, v23
	s_waitcnt vmcnt(20)
	v_dot8_i32_i4 v23, v86, v73, 0
	buffer_load_dwordx2 v[36:37], v192, s[52:55], s0 offen
	v_readlane_b32 s0, v14, 13
	s_lshl_b32 s0, s0, 9
	v_dot8_i32_i4 v26, v86, v75, 0
	v_dot8_i32_i4 v23, v87, v77, v23
	v_dot8_i32_i4 v26, v87, v108, v26
	buffer_load_dwordx2 v[24:25], v192, s[52:55], s0 offen
	v_readlane_b32 s0, v14, 14
	s_lshl_b32 s0, s0, 9
	v_lshl_add_u32 v23, v23, 4, v26
	s_waitcnt vmcnt(21)
	v_dot8_i32_i4 v26, v54, v73, 0
	v_dot8_i32_i4 v27, v54, v75, 0
	buffer_load_dwordx2 v[18:19], v192, s[52:55], s0 offen
	v_readlane_b32 s0, v14, 15
	s_lshl_b32 s0, s0, 9
	v_dot8_i32_i4 v26, v55, v77, v26
	v_dot8_i32_i4 v27, v55, v108, v27
	s_waitcnt vmcnt(21)
	v_dot8_i32_i4 v30, v48, v75, 0
	buffer_load_dwordx2 v[28:29], v192, s[52:55], s0 offen
	v_lshl_add_u32 v26, v26, 4, v27
	v_dot8_i32_i4 v27, v48, v73, 0
	v_dot8_i32_i4 v27, v49, v77, v27
	v_dot8_i32_i4 v30, v49, v108, v30
	s_waitcnt vmcnt(21)
	v_dot8_i32_i4 v31, v42, v75, 0
	v_dot8_i32_i4 v31, v43, v108, v31
	v_lshl_add_u32 v27, v27, 4, v30
	v_dot8_i32_i4 v30, v42, v73, 0
	v_dot8_i32_i4 v30, v43, v77, v30
	s_waitcnt vmcnt(20)
	v_dot8_i32_i4 v42, v50, v75, 0
	v_dot8_i32_i4 v42, v51, v108, v42
	v_lshl_add_u32 v30, v30, 4, v31
	v_dot8_i32_i4 v31, v50, v73, 0
	v_dot8_i32_i4 v31, v51, v77, v31
	s_waitcnt vmcnt(19)
	v_dot8_i32_i4 v43, v38, v75, 0
	v_dot8_i32_i4 v43, v39, v108, v43
	v_lshl_add_u32 v31, v31, 4, v42
	v_dot8_i32_i4 v42, v38, v73, 0
	v_dot8_i32_i4 v42, v39, v77, v42
	s_waitcnt vmcnt(18)
	v_dot8_i32_i4 v39, v32, v73, 0
	v_dot8_i32_i4 v39, v33, v77, v39
	v_lshl_add_u32 v38, v42, 4, v43
	v_dot8_i32_i4 v42, v32, v75, 0
	v_dot8_i32_i4 v42, v33, v108, v42
	s_waitcnt vmcnt(17)
	v_dot8_i32_i4 v33, v20, v73, 0
	v_cvt_f32_i32_e32 v5, v5
	v_lshl_add_u32 v32, v39, 4, v42
	v_dot8_i32_i4 v39, v20, v75, 0
	v_cvt_f32_i32_e32 v9, v9
	v_cvt_f32_i32_e32 v11, v11
	v_cvt_f32_i32_e32 v13, v13
	v_dot8_i32_i4 v33, v21, v77, v33
	v_dot8_i32_i4 v39, v21, v108, v39
	v_cvt_f32_i32_e32 v15, v15
	v_cvt_f32_i32_e32 v17, v17
	s_nop 0
	v_lshl_add_u32 v20, v33, 4, v39
	s_waitcnt vmcnt(16)
	v_dot8_i32_i4 v21, v34, v73, 0
	v_dot8_i32_i4 v33, v34, v75, 0
	v_dot8_i32_i4 v21, v35, v77, v21
	v_dot8_i32_i4 v33, v35, v108, v33
	v_cvt_f32_i32_e32 v22, v22
	v_cvt_f32_i32_e32 v23, v23
	v_cvt_f32_i32_e32 v26, v26
	v_lshl_add_u32 v21, v21, 4, v33
	v_cndmask_b32_e64 v33, v9, v5, s[40:41]
	v_cndmask_b32_e64 v5, v5, v9, s[40:41]
	v_cndmask_b32_e64 v9, v13, v11, s[40:41]
	v_cndmask_b32_e64 v11, v11, v13, s[40:41]
	ds_swizzle_b32 v11, v11 offset:swizzle(SWAP,1)
	v_cndmask_b32_e64 v13, v15, v17, s[40:41]
	v_cvt_f32_i32_e32 v27, v27
	ds_swizzle_b32 v13, v13 offset:swizzle(SWAP,1)
	v_cvt_f32_i32_e32 v30, v30
	v_cvt_f32_i32_e32 v31, v31
	v_cvt_f32_i32_e32 v38, v38
	v_cvt_f32_i32_e32 v32, v32
	s_waitcnt lgkmcnt(1)
	v_add_f32_e32 v9, v9, v11
	v_cndmask_b32_e64 v11, v17, v15, s[40:41]
	v_cndmask_b32_e64 v15, v22, v23, s[40:41]
	ds_swizzle_b32 v15, v15 offset:swizzle(SWAP,1)
	v_cndmask_b32_e64 v17, v26, v27, s[40:41]
	s_waitcnt lgkmcnt(1)
	v_add_f32_e32 v11, v11, v13
	v_cndmask_b32_e64 v13, v23, v22, s[40:41]
	ds_swizzle_b32 v17, v17 offset:swizzle(SWAP,1)
	v_cndmask_b32_e64 v22, v30, v31, s[40:41]
	ds_swizzle_b32 v22, v22 offset:swizzle(SWAP,1)
	v_cndmask_b32_e64 v23, v38, v32, s[40:41]
	ds_swizzle_b32 v5, v5 offset:swizzle(SWAP,1)
	ds_swizzle_b32 v23, v23 offset:swizzle(SWAP,1)
	v_cvt_f32_i32_e32 v20, v20
	v_cvt_f32_i32_e32 v21, v21
	s_waitcnt lgkmcnt(4)
	v_add_f32_e32 v13, v13, v15
	v_cndmask_b32_e64 v15, v27, v26, s[40:41]
	s_waitcnt lgkmcnt(3)
	v_add_f32_e32 v15, v15, v17
	v_cndmask_b32_e64 v17, v31, v30, s[40:41]
	s_waitcnt lgkmcnt(2)
	v_add_f32_e32 v17, v17, v22
	v_cndmask_b32_e64 v22, v32, v38, s[40:41]
	s_waitcnt lgkmcnt(1)
	v_add_f32_e32 v5, v33, v5
	s_waitcnt lgkmcnt(0)
	v_add_f32_e32 v22, v22, v23
	v_cndmask_b32_e64 v23, v21, v20, s[40:41]
	v_cndmask_b32_e64 v20, v20, v21, s[40:41]
	ds_swizzle_b32 v20, v20 offset:swizzle(SWAP,1)
	v_cndmask_b32_e64 v21, v9, v5, s[42:43]
	v_cndmask_b32_e64 v5, v5, v9, s[42:43]
	v_cndmask_b32_e64 v9, v13, v11, s[42:43]
	v_cndmask_b32_e64 v11, v11, v13, s[42:43]
	ds_swizzle_b32 v11, v11 offset:swizzle(SWAP,2)
	s_waitcnt lgkmcnt(1)
	v_add_f32_e32 v20, v23, v20
	v_cndmask_b32_e64 v13, v15, v17, s[42:43]
	ds_swizzle_b32 v13, v13 offset:swizzle(SWAP,2)
	ds_swizzle_b32 v5, v5 offset:swizzle(SWAP,2)
	s_waitcnt lgkmcnt(2)
	v_add_f32_e32 v9, v9, v11
	v_cndmask_b32_e64 v11, v17, v15, s[42:43]
	v_cndmask_b32_e64 v15, v22, v20, s[42:43]
	ds_swizzle_b32 v15, v15 offset:swizzle(SWAP,2)
	s_waitcnt lgkmcnt(2)
	v_add_f32_e32 v11, v11, v13
	v_cndmask_b32_e64 v13, v20, v22, s[42:43]
	s_waitcnt lgkmcnt(1)
	v_add_f32_e32 v5, v21, v5
	s_waitcnt lgkmcnt(0)
	v_add_f32_e32 v13, v13, v15
	v_cndmask_b32_e64 v15, v9, v5, s[44:45]
	v_cndmask_b32_e64 v5, v5, v9, s[44:45]
	v_cndmask_b32_e64 v9, v13, v11, s[44:45]
	v_cndmask_b32_e64 v11, v11, v13, s[44:45]
	ds_swizzle_b32 v5, v5 offset:swizzle(SWAP,4)
	ds_swizzle_b32 v11, v11 offset:swizzle(SWAP,4)
	s_waitcnt lgkmcnt(1)
	v_add_f32_e32 v5, v15, v5
	s_waitcnt lgkmcnt(0)
	v_add_f32_e32 v9, v9, v11
	v_cndmask_b32_e64 v11, v9, v5, s[46:47]
	v_cndmask_b32_e64 v5, v5, v9, s[46:47]
	ds_swizzle_b32 v5, v5 offset:swizzle(SWAP,8)
	s_waitcnt lgkmcnt(0)
	v_add_f32_e32 v5, v11, v5
	ds_swizzle_b32 v9, v5 offset:swizzle(SWAP,16)
	s_waitcnt lgkmcnt(0)
	v_add_f32_e32 v5, v5, v9
	ds_bpermute_b32 v9, v0, v5
	s_and_saveexec_b64 s[0:1], s[48:49]
	s_cbranch_execz .LBB0_545
	v_ashrrev_i32_e32 v17, 31, v16
	v_lshlrev_b64 v[16:17], 2, v[16:17]
	v_lshl_add_u64 v[20:21], s[8:9], 0, v[16:17]
	v_mov_b32_e32 v11, v130
	v_lshl_add_u64 v[16:17], s[10:11], 0, v[16:17]
	v_mov_b32_e32 v13, v146
	v_mov_b32_e32 v15, v138
	s_waitcnt lgkmcnt(0)
	v_add_f32_e32 v5, v5, v9
	v_mul_f32_e32 v5, v5, v11
	v_mul_f32_e32 v5, v3, v5
	v_mul_f32_e32 v11, 0x3d372713, v5
	v_mul_f32_e32 v11, v5, v11
	v_mul_f32_e32 v9, 0.5, v5
	v_fmac_f32_e32 v5, v5, v11
	v_mul_f32_e32 v5, 0x3f4c422a, v5
	v_add_f32_e32 v5, v5, v5
	v_mul_f32_e32 v5, 0x3fb8aa3b, v5
	v_exp_f32_e32 v5, v5
	s_nop 0
	v_add_f32_e32 v5, 1.0, v5
	v_rcp_f32_e32 v5, v5
	s_nop 0
	v_fma_f32 v5, v5, -2.0, 1.0
	v_add_f32_e32 v5, 1.0, v5
	v_mul_f32_e32 v5, v9, v5
	v_mul_f32_e32 v5, v13, v5
	v_mul_f32_e32 v5, v15, v5
	ds_write_b32 v109, v5 offset:128
.LBB0_545:
	s_or_b64 exec, exec, s[0:1]
	v_readlane_b32 s0, v12, 0
	s_lshl_b32 s0, s0, 9
	s_waitcnt lgkmcnt(0)
	s_waitcnt vmcnt(15)
	v_dot8_i32_i4 v5, v96, v73, 0
	v_dot8_i32_i4 v9, v96, v75, 0
	buffer_load_dwordx2 v[94:95], v192, s[52:55], s0 offen
	v_readlane_b32 s0, v12, 1
	s_lshl_b32 s0, s0, 9
	v_dot8_i32_i4 v5, v97, v77, v5
	v_dot8_i32_i4 v9, v97, v108, v9
	s_waitcnt vmcnt(15)
	v_dot8_i32_i4 v11, v104, v75, 0
	buffer_load_dwordx2 v[86:87], v192, s[52:55], s0 offen
	v_readlane_b32 s0, v12, 2
	s_lshl_b32 s0, s0, 9
	v_lshl_add_u32 v5, v5, 4, v9
	v_dot8_i32_i4 v9, v104, v73, 0
	v_dot8_i32_i4 v9, v105, v77, v9
	buffer_load_dwordx2 v[84:85], v192, s[52:55], s0 offen
	v_readlane_b32 s0, v12, 3
	s_lshl_b32 s0, s0, 9
	v_dot8_i32_i4 v11, v105, v108, v11
	s_waitcnt vmcnt(16)
	v_dot8_i32_i4 v13, v92, v75, 0
	v_dot8_i32_i4 v13, v93, v108, v13
	buffer_load_dwordx2 v[90:91], v192, s[52:55], s0 offen
	v_readlane_b32 s0, v12, 4
	s_lshl_b32 s0, s0, 9
	v_lshl_add_u32 v9, v9, 4, v11
	v_dot8_i32_i4 v11, v92, v73, 0
	v_dot8_i32_i4 v11, v93, v77, v11
	buffer_load_dwordx2 v[78:79], v192, s[52:55], s0 offen
	v_readlane_b32 s0, v12, 5
	s_lshl_b32 s0, s0, 9
	v_lshl_add_u32 v11, v11, 4, v13
	s_waitcnt vmcnt(17)
	v_dot8_i32_i4 v13, v106, v73, 0
	buffer_load_dwordx2 v[50:51], v192, s[52:55], s0 offen
	v_readlane_b32 s0, v12, 6
	s_lshl_b32 s0, s0, 9
	v_dot8_i32_i4 v15, v106, v75, 0
	v_dot8_i32_i4 v13, v107, v77, v13
	v_dot8_i32_i4 v15, v107, v108, v15
	buffer_load_dwordx2 v[48:49], v192, s[52:55], s0 offen
	v_readlane_b32 s0, v12, 7
	s_lshl_b32 s0, s0, 9
	v_lshl_add_u32 v13, v13, 4, v15
	s_waitcnt vmcnt(18)
	v_dot8_i32_i4 v15, v88, v73, 0
	v_dot8_i32_i4 v32, v88, v75, 0
	buffer_load_dwordx2 v[54:55], v192, s[52:55], s0 offen
	v_readlane_b32 s0, v12, 8
	s_lshl_b32 s0, s0, 9
	v_dot8_i32_i4 v15, v89, v77, v15
	v_dot8_i32_i4 v32, v89, v108, v32
	s_waitcnt vmcnt(18)
	v_dot8_i32_i4 v33, v80, v75, 0
	buffer_load_dwordx2 v[42:43], v192, s[52:55], s0 offen
	v_readlane_b32 s0, v12, 9
	s_lshl_b32 s0, s0, 9
	v_lshl_add_u32 v15, v15, 4, v32
	v_dot8_i32_i4 v32, v80, v73, 0
	v_dot8_i32_i4 v32, v81, v77, v32
	buffer_load_dwordx2 v[34:35], v192, s[52:55], s0 offen
	v_readlane_b32 s0, v12, 10
	s_lshl_b32 s0, s0, 9
	v_dot8_i32_i4 v33, v81, v108, v33
	s_waitcnt vmcnt(19)
	v_dot8_i32_i4 v80, v56, v75, 0
	v_dot8_i32_i4 v80, v57, v108, v80
	buffer_load_dwordx2 v[30:31], v192, s[52:55], s0 offen
	v_readlane_b32 s0, v12, 11
	s_lshl_b32 s0, s0, 9
	v_lshl_add_u32 v32, v32, 4, v33
	v_dot8_i32_i4 v33, v56, v73, 0
	v_dot8_i32_i4 v33, v57, v77, v33
	buffer_load_dwordx2 v[38:39], v192, s[52:55], s0 offen
	v_readlane_b32 s0, v12, 12
	s_lshl_b32 s0, s0, 9
	s_waitcnt vmcnt(20)
	v_dot8_i32_i4 v56, v82, v73, 0
	v_dot8_i32_i4 v57, v82, v75, 0
	buffer_load_dwordx2 v[26:27], v192, s[52:55], s0 offen
	v_readlane_b32 s0, v12, 13
	s_lshl_b32 s0, s0, 9
	v_dot8_i32_i4 v56, v83, v77, v56
	v_dot8_i32_i4 v57, v83, v108, v57
	v_lshl_add_u32 v33, v33, 4, v80
	buffer_load_dwordx2 v[20:21], v192, s[52:55], s0 offen
	v_readlane_b32 s0, v12, 14
	s_lshl_b32 s0, s0, 9
	v_lshl_add_u32 v56, v56, 4, v57
	s_waitcnt vmcnt(21)
	v_dot8_i32_i4 v57, v52, v73, 0
	v_dot8_i32_i4 v80, v52, v75, 0
	buffer_load_dwordx2 v[16:17], v192, s[52:55], s0 offen
	v_readlane_b32 s0, v12, 15
	s_lshl_b32 s0, s0, 9
	v_dot8_i32_i4 v57, v53, v77, v57
	v_dot8_i32_i4 v80, v53, v108, v80
	s_waitcnt vmcnt(21)
	v_dot8_i32_i4 v53, v44, v73, 0
	buffer_load_dwordx2 v[22:23], v192, s[52:55], s0 offen
	v_lshl_add_u32 v52, v57, 4, v80
	v_dot8_i32_i4 v57, v44, v75, 0
	v_dot8_i32_i4 v53, v45, v77, v53
	v_dot8_i32_i4 v57, v45, v108, v57
	s_waitcnt vmcnt(21)
	v_dot8_i32_i4 v45, v40, v73, 0
	v_dot8_i32_i4 v45, v41, v77, v45
	v_lshl_add_u32 v44, v53, 4, v57
	v_dot8_i32_i4 v53, v40, v75, 0
	v_dot8_i32_i4 v53, v41, v108, v53
	s_waitcnt vmcnt(20)
	v_dot8_i32_i4 v41, v46, v73, 0
	v_dot8_i32_i4 v41, v47, v77, v41
	v_lshl_add_u32 v40, v45, 4, v53
	v_dot8_i32_i4 v45, v46, v75, 0
	v_dot8_i32_i4 v45, v47, v108, v45
	s_waitcnt vmcnt(19)
	v_dot8_i32_i4 v46, v36, v75, 0
	v_dot8_i32_i4 v46, v37, v108, v46
	v_lshl_add_u32 v41, v41, 4, v45
	v_dot8_i32_i4 v45, v36, v73, 0
	v_dot8_i32_i4 v45, v37, v77, v45
	s_waitcnt vmcnt(18)
	v_dot8_i32_i4 v37, v24, v73, 0
	v_dot8_i32_i4 v37, v25, v77, v37
	v_lshl_add_u32 v36, v45, 4, v46
	v_dot8_i32_i4 v45, v24, v75, 0
	v_dot8_i32_i4 v45, v25, v108, v45
	s_waitcnt vmcnt(17)
	v_dot8_i32_i4 v25, v18, v73, 0
	v_cvt_f32_i32_e32 v5, v5
	v_lshl_add_u32 v24, v37, 4, v45
	v_dot8_i32_i4 v37, v18, v75, 0
	v_cvt_f32_i32_e32 v9, v9
	v_cvt_f32_i32_e32 v11, v11
	v_cvt_f32_i32_e32 v13, v13
	v_dot8_i32_i4 v25, v19, v77, v25
	v_dot8_i32_i4 v37, v19, v108, v37
	s_waitcnt vmcnt(16)
	v_dot8_i32_i4 v19, v28, v73, 0
	v_dot8_i32_i4 v19, v29, v77, v19
	v_lshl_add_u32 v18, v25, 4, v37
	v_dot8_i32_i4 v25, v28, v75, 0
	v_dot8_i32_i4 v25, v29, v108, v25
	v_cvt_f32_i32_e32 v15, v15
	v_cvt_f32_i32_e32 v32, v32
	v_cvt_f32_i32_e32 v33, v33
	v_lshl_add_u32 v19, v19, 4, v25
	v_cndmask_b32_e64 v25, v9, v5, s[40:41]
	v_cndmask_b32_e64 v5, v5, v9, s[40:41]
	v_cndmask_b32_e64 v9, v13, v11, s[40:41]
	v_cndmask_b32_e64 v11, v11, v13, s[40:41]
	ds_swizzle_b32 v11, v11 offset:swizzle(SWAP,1)
	v_cvt_f32_i32_e32 v56, v56
	ds_swizzle_b32 v5, v5 offset:swizzle(SWAP,1)
	v_cvt_f32_i32_e32 v52, v52
	v_cvt_f32_i32_e32 v44, v44
	v_cvt_f32_i32_e32 v40, v40
	v_cvt_f32_i32_e32 v41, v41
	v_cndmask_b32_e64 v13, v15, v32, s[40:41]
	s_waitcnt lgkmcnt(1)
	v_add_f32_e32 v9, v9, v11
	v_cndmask_b32_e64 v11, v32, v15, s[40:41]
	ds_swizzle_b32 v13, v13 offset:swizzle(SWAP,1)
	v_cndmask_b32_e64 v15, v33, v56, s[40:41]
	s_waitcnt lgkmcnt(1)
	v_add_f32_e32 v5, v25, v5
	ds_swizzle_b32 v15, v15 offset:swizzle(SWAP,1)
	v_cndmask_b32_e64 v25, v52, v44, s[40:41]
	ds_swizzle_b32 v25, v25 offset:swizzle(SWAP,1)
	v_cndmask_b32_e64 v28, v40, v41, s[40:41]
	ds_swizzle_b32 v28, v28 offset:swizzle(SWAP,1)
	v_cvt_f32_i32_e32 v36, v36
	v_cvt_f32_i32_e32 v24, v24
	s_waitcnt lgkmcnt(3)
	v_add_f32_e32 v11, v11, v13
	v_cndmask_b32_e64 v13, v56, v33, s[40:41]
	s_waitcnt lgkmcnt(2)
	v_add_f32_e32 v13, v13, v15
	v_cndmask_b32_e64 v15, v44, v52, s[40:41]
	s_waitcnt lgkmcnt(1)
	v_add_f32_e32 v15, v15, v25
	v_cndmask_b32_e64 v25, v41, v40, s[40:41]
	s_waitcnt lgkmcnt(0)
	v_add_f32_e32 v25, v25, v28
	v_cndmask_b32_e64 v28, v24, v36, s[40:41]
	v_cndmask_b32_e64 v24, v36, v24, s[40:41]
	ds_swizzle_b32 v24, v24 offset:swizzle(SWAP,1)
	v_cvt_f32_i32_e32 v18, v18
	v_cvt_f32_i32_e32 v19, v19
	s_waitcnt lgkmcnt(0)
	v_add_f32_e32 v24, v28, v24
	v_cndmask_b32_e64 v28, v19, v18, s[40:41]
	v_cndmask_b32_e64 v18, v18, v19, s[40:41]
	ds_swizzle_b32 v18, v18 offset:swizzle(SWAP,1)
	v_cndmask_b32_e64 v19, v9, v5, s[42:43]
	v_cndmask_b32_e64 v5, v5, v9, s[42:43]
	v_cndmask_b32_e64 v9, v13, v11, s[42:43]
	v_cndmask_b32_e64 v11, v11, v13, s[42:43]
	ds_swizzle_b32 v11, v11 offset:swizzle(SWAP,2)
	s_waitcnt lgkmcnt(1)
	v_add_f32_e32 v18, v28, v18
	v_cndmask_b32_e64 v13, v15, v25, s[42:43]
	ds_swizzle_b32 v13, v13 offset:swizzle(SWAP,2)
	ds_swizzle_b32 v5, v5 offset:swizzle(SWAP,2)
	s_waitcnt lgkmcnt(2)
	v_add_f32_e32 v9, v9, v11
	v_cndmask_b32_e64 v11, v25, v15, s[42:43]
	v_cndmask_b32_e64 v15, v24, v18, s[42:43]
	ds_swizzle_b32 v15, v15 offset:swizzle(SWAP,2)
	s_waitcnt lgkmcnt(2)
	v_add_f32_e32 v11, v11, v13
	v_cndmask_b32_e64 v13, v18, v24, s[42:43]
	s_waitcnt lgkmcnt(1)
	v_add_f32_e32 v5, v19, v5
	s_waitcnt lgkmcnt(0)
	v_add_f32_e32 v13, v13, v15
	v_cndmask_b32_e64 v15, v9, v5, s[44:45]
	v_cndmask_b32_e64 v5, v5, v9, s[44:45]
	v_cndmask_b32_e64 v9, v13, v11, s[44:45]
	v_cndmask_b32_e64 v11, v11, v13, s[44:45]
	ds_swizzle_b32 v5, v5 offset:swizzle(SWAP,4)
	ds_swizzle_b32 v11, v11 offset:swizzle(SWAP,4)
	s_waitcnt lgkmcnt(1)
	v_add_f32_e32 v5, v15, v5
	s_waitcnt lgkmcnt(0)
	v_add_f32_e32 v9, v9, v11
	v_cndmask_b32_e64 v11, v9, v5, s[46:47]
	v_cndmask_b32_e64 v5, v5, v9, s[46:47]
	ds_swizzle_b32 v5, v5 offset:swizzle(SWAP,8)
	s_waitcnt lgkmcnt(0)
	v_add_f32_e32 v5, v11, v5
	ds_swizzle_b32 v9, v5 offset:swizzle(SWAP,16)
	s_waitcnt lgkmcnt(0)
	v_add_f32_e32 v5, v5, v9
	ds_bpermute_b32 v9, v0, v5
	s_and_saveexec_b64 s[0:1], s[48:49]
	s_cbranch_execz .LBB0_547
	v_ashrrev_i32_e32 v15, 31, v14
	v_lshlrev_b64 v[14:15], 2, v[14:15]
	v_lshl_add_u64 v[18:19], s[8:9], 0, v[14:15]
	v_mov_b32_e32 v11, v131
	v_lshl_add_u64 v[14:15], s[10:11], 0, v[14:15]
	v_mov_b32_e32 v13, v147
	s_nop 0
	v_mov_b32_e32 v14, v139
	s_waitcnt lgkmcnt(0)
	v_add_f32_e32 v5, v5, v9
	v_mul_f32_e32 v5, v5, v11
	v_mul_f32_e32 v5, v3, v5
	v_mul_f32_e32 v11, 0x3d372713, v5
	v_mul_f32_e32 v11, v5, v11
	v_mul_f32_e32 v9, 0.5, v5
	v_fmac_f32_e32 v5, v5, v11
	v_mul_f32_e32 v5, 0x3f4c422a, v5
	v_add_f32_e32 v5, v5, v5
	v_mul_f32_e32 v5, 0x3fb8aa3b, v5
	v_exp_f32_e32 v5, v5
	s_nop 0
	v_add_f32_e32 v5, 1.0, v5
	v_rcp_f32_e32 v5, v5
	s_nop 0
	v_fma_f32 v5, v5, -2.0, 1.0
	v_add_f32_e32 v5, 1.0, v5
	v_mul_f32_e32 v5, v9, v5
	v_mul_f32_e32 v5, v13, v5
	v_mul_f32_e32 v5, v14, v5
	ds_write_b32 v109, v5 offset:192
.LBB0_547:
	s_or_b64 exec, exec, s[0:1]
	v_readlane_b32 s0, v10, 0
	s_lshl_b32 s0, s0, 9
	s_waitcnt lgkmcnt(0)
	s_waitcnt vmcnt(15)
	v_dot8_i32_i4 v5, v94, v73, 0
	v_dot8_i32_i4 v9, v94, v75, 0
	buffer_load_dwordx2 v[92:93], v192, s[52:55], s0 offen
	v_readlane_b32 s0, v10, 1
	s_lshl_b32 s0, s0, 9
	v_dot8_i32_i4 v5, v95, v77, v5
	v_dot8_i32_i4 v9, v95, v108, v9
	s_waitcnt vmcnt(15)
	v_dot8_i32_i4 v11, v86, v75, 0
	buffer_load_dwordx2 v[96:97], v192, s[52:55], s0 offen
	v_readlane_b32 s0, v10, 2
	s_lshl_b32 s0, s0, 9
	v_lshl_add_u32 v5, v5, 4, v9
	v_dot8_i32_i4 v9, v86, v73, 0
	v_dot8_i32_i4 v9, v87, v77, v9
	buffer_load_dwordx2 v[88:89], v192, s[52:55], s0 offen
	v_readlane_b32 s0, v10, 3
	s_lshl_b32 s0, s0, 9
	v_dot8_i32_i4 v11, v87, v108, v11
	s_waitcnt vmcnt(16)
	v_dot8_i32_i4 v13, v84, v75, 0
	v_dot8_i32_i4 v13, v85, v108, v13
	buffer_load_dwordx2 v[98:99], v192, s[52:55], s0 offen
	v_readlane_b32 s0, v10, 4
	s_lshl_b32 s0, s0, 9
	v_lshl_add_u32 v9, v9, 4, v11
	v_dot8_i32_i4 v11, v84, v73, 0
	v_dot8_i32_i4 v11, v85, v77, v11
	buffer_load_dwordx2 v[82:83], v192, s[52:55], s0 offen
	v_readlane_b32 s0, v10, 5
	s_lshl_b32 s0, s0, 9
	v_lshl_add_u32 v11, v11, 4, v13
	s_waitcnt vmcnt(17)
	v_dot8_i32_i4 v13, v90, v73, 0
	buffer_load_dwordx2 v[56:57], v192, s[52:55], s0 offen
	v_readlane_b32 s0, v10, 6
	s_lshl_b32 s0, s0, 9
	v_dot8_i32_i4 v18, v90, v75, 0
	v_dot8_i32_i4 v13, v91, v77, v13
	v_dot8_i32_i4 v18, v91, v108, v18
	buffer_load_dwordx2 v[52:53], v192, s[52:55], s0 offen
	v_readlane_b32 s0, v10, 7
	s_lshl_b32 s0, s0, 9
	v_lshl_add_u32 v13, v13, 4, v18
	s_waitcnt vmcnt(18)
	v_dot8_i32_i4 v18, v78, v73, 0
	v_dot8_i32_i4 v19, v78, v75, 0
	buffer_load_dwordx2 v[80:81], v192, s[52:55], s0 offen
	v_readlane_b32 s0, v10, 8
	s_lshl_b32 s0, s0, 9
	v_dot8_i32_i4 v18, v79, v77, v18
	v_dot8_i32_i4 v19, v79, v108, v19
	s_waitcnt vmcnt(18)
	v_dot8_i32_i4 v78, v50, v75, 0
	buffer_load_dwordx2 v[46:47], v192, s[52:55], s0 offen
	v_readlane_b32 s0, v10, 9
	s_lshl_b32 s0, s0, 9
	v_lshl_add_u32 v18, v18, 4, v19
	v_dot8_i32_i4 v19, v50, v73, 0
	v_dot8_i32_i4 v19, v51, v77, v19
	buffer_load_dwordx2 v[40:41], v192, s[52:55], s0 offen
	v_readlane_b32 s0, v10, 10
	s_lshl_b32 s0, s0, 9
	v_dot8_i32_i4 v78, v51, v108, v78
	s_waitcnt vmcnt(19)
	v_dot8_i32_i4 v50, v48, v73, 0
	buffer_load_dwordx2 v[36:37], v192, s[52:55], s0 offen
	v_readlane_b32 s0, v10, 11
	s_lshl_b32 s0, s0, 9
	v_dot8_i32_i4 v51, v48, v75, 0
	v_dot8_i32_i4 v50, v49, v77, v50
	v_dot8_i32_i4 v51, v49, v108, v51
	buffer_load_dwordx2 v[44:45], v192, s[52:55], s0 offen
	v_readlane_b32 s0, v10, 12
	s_lshl_b32 s0, s0, 9
	v_lshl_add_u32 v48, v50, 4, v51
	s_waitcnt vmcnt(20)
	v_dot8_i32_i4 v49, v54, v73, 0
	v_dot8_i32_i4 v50, v54, v75, 0
	buffer_load_dwordx2 v[32:33], v192, s[52:55], s0 offen
	v_readlane_b32 s0, v10, 13
	s_lshl_b32 s0, s0, 9
	v_dot8_i32_i4 v49, v55, v77, v49
	v_dot8_i32_i4 v50, v55, v108, v50
	s_waitcnt vmcnt(20)
	v_dot8_i32_i4 v51, v42, v75, 0
	buffer_load_dwordx2 v[24:25], v192, s[52:55], s0 offen
	v_readlane_b32 s0, v10, 14
	s_lshl_b32 s0, s0, 9
	v_lshl_add_u32 v49, v49, 4, v50
	v_dot8_i32_i4 v50, v42, v73, 0
	v_dot8_i32_i4 v50, v43, v77, v50
	buffer_load_dwordx2 v[14:15], v192, s[52:55], s0 offen
	v_readlane_b32 s0, v10, 15
	s_lshl_b32 s0, s0, 9
	v_dot8_i32_i4 v51, v43, v108, v51
	s_waitcnt vmcnt(21)
	v_dot8_i32_i4 v43, v34, v73, 0
	v_dot8_i32_i4 v43, v35, v77, v43
	buffer_load_dwordx2 v[28:29], v192, s[52:55], s0 offen
	v_lshl_add_u32 v42, v50, 4, v51
	v_dot8_i32_i4 v50, v34, v75, 0
	v_dot8_i32_i4 v50, v35, v108, v50
	s_waitcnt vmcnt(21)
	v_dot8_i32_i4 v35, v30, v73, 0
	v_dot8_i32_i4 v35, v31, v77, v35
	v_lshl_add_u32 v34, v43, 4, v50
	v_dot8_i32_i4 v43, v30, v75, 0
	v_dot8_i32_i4 v43, v31, v108, v43
	s_waitcnt vmcnt(20)
	v_dot8_i32_i4 v31, v38, v73, 0
	v_dot8_i32_i4 v31, v39, v77, v31
	v_lshl_add_u32 v30, v35, 4, v43
	v_dot8_i32_i4 v35, v38, v75, 0
	v_dot8_i32_i4 v35, v39, v108, v35
	s_waitcnt vmcnt(19)
	v_dot8_i32_i4 v38, v26, v75, 0
	v_dot8_i32_i4 v38, v27, v108, v38
	v_lshl_add_u32 v31, v31, 4, v35
	v_dot8_i32_i4 v35, v26, v73, 0
	v_dot8_i32_i4 v35, v27, v77, v35
	s_waitcnt vmcnt(18)
	v_dot8_i32_i4 v27, v20, v73, 0
	v_dot8_i32_i4 v27, v21, v77, v27
	v_lshl_add_u32 v26, v35, 4, v38
	v_dot8_i32_i4 v35, v20, v75, 0
	v_dot8_i32_i4 v35, v21, v108, v35
	s_waitcnt vmcnt(17)
	v_dot8_i32_i4 v21, v16, v73, 0
	v_cvt_f32_i32_e32 v5, v5
	v_lshl_add_u32 v20, v27, 4, v35
	v_dot8_i32_i4 v27, v16, v75, 0
	v_cvt_f32_i32_e32 v9, v9
	v_cvt_f32_i32_e32 v11, v11
	v_cvt_f32_i32_e32 v13, v13
	v_dot8_i32_i4 v21, v17, v77, v21
	v_dot8_i32_i4 v27, v17, v108, v27
	s_waitcnt vmcnt(16)
	v_dot8_i32_i4 v17, v22, v73, 0
	v_dot8_i32_i4 v17, v23, v77, v17
	v_lshl_add_u32 v16, v21, 4, v27
	v_dot8_i32_i4 v21, v22, v75, 0
	v_dot8_i32_i4 v21, v23, v108, v21
	v_lshl_add_u32 v19, v19, 4, v78
	v_cvt_f32_i32_e32 v18, v18
	v_cvt_f32_i32_e32 v19, v19
	v_lshl_add_u32 v17, v17, 4, v21
	v_cndmask_b32_e64 v21, v9, v5, s[40:41]
	v_cndmask_b32_e64 v5, v5, v9, s[40:41]
	v_cndmask_b32_e64 v9, v13, v11, s[40:41]
	v_cndmask_b32_e64 v11, v11, v13, s[40:41]
	ds_swizzle_b32 v11, v11 offset:swizzle(SWAP,1)
	v_cvt_f32_i32_e32 v48, v48
	v_cvt_f32_i32_e32 v49, v49
	v_cvt_f32_i32_e32 v42, v42
	v_cvt_f32_i32_e32 v34, v34
	ds_swizzle_b32 v5, v5 offset:swizzle(SWAP,1)
	v_cvt_f32_i32_e32 v30, v30
	v_cvt_f32_i32_e32 v31, v31
	v_cndmask_b32_e64 v13, v18, v19, s[40:41]
	s_waitcnt lgkmcnt(1)
	v_add_f32_e32 v9, v9, v11
	v_cndmask_b32_e64 v11, v19, v18, s[40:41]
	ds_swizzle_b32 v13, v13 offset:swizzle(SWAP,1)
	v_cndmask_b32_e64 v18, v48, v49, s[40:41]
	ds_swizzle_b32 v18, v18 offset:swizzle(SWAP,1)
	v_cndmask_b32_e64 v19, v42, v34, s[40:41]
	s_waitcnt lgkmcnt(2)
	v_add_f32_e32 v5, v21, v5
	ds_swizzle_b32 v19, v19 offset:swizzle(SWAP,1)
	v_cndmask_b32_e64 v21, v30, v31, s[40:41]
	ds_swizzle_b32 v21, v21 offset:swizzle(SWAP,1)
	v_cvt_f32_i32_e32 v26, v26
	v_cvt_f32_i32_e32 v20, v20
	s_waitcnt lgkmcnt(3)
	v_add_f32_e32 v11, v11, v13
	v_cndmask_b32_e64 v13, v49, v48, s[40:41]
	s_waitcnt lgkmcnt(2)
	v_add_f32_e32 v13, v13, v18
	v_cndmask_b32_e64 v18, v34, v42, s[40:41]
	s_waitcnt lgkmcnt(1)
	v_add_f32_e32 v18, v18, v19
	v_cndmask_b32_e64 v19, v31, v30, s[40:41]
	s_waitcnt lgkmcnt(0)
	v_add_f32_e32 v19, v19, v21
	v_cndmask_b32_e64 v21, v20, v26, s[40:41]
	v_cndmask_b32_e64 v20, v26, v20, s[40:41]
	ds_swizzle_b32 v20, v20 offset:swizzle(SWAP,1)
	v_cvt_f32_i32_e32 v16, v16
	v_cvt_f32_i32_e32 v17, v17
	s_waitcnt lgkmcnt(0)
	v_add_f32_e32 v20, v21, v20
	v_cndmask_b32_e64 v21, v17, v16, s[40:41]
	v_cndmask_b32_e64 v16, v16, v17, s[40:41]
	v_cndmask_b32_e64 v17, v9, v5, s[42:43]
	v_cndmask_b32_e64 v5, v5, v9, s[42:43]
	v_cndmask_b32_e64 v9, v13, v11, s[42:43]
	v_cndmask_b32_e64 v11, v11, v13, s[42:43]
	ds_swizzle_b32 v16, v16 offset:swizzle(SWAP,1)
	ds_swizzle_b32 v11, v11 offset:swizzle(SWAP,2)
	v_cndmask_b32_e64 v13, v18, v19, s[42:43]
	ds_swizzle_b32 v13, v13 offset:swizzle(SWAP,2)
	ds_swizzle_b32 v5, v5 offset:swizzle(SWAP,2)
	s_waitcnt lgkmcnt(3)
	v_add_f32_e32 v16, v21, v16
	s_waitcnt lgkmcnt(2)
	v_add_f32_e32 v9, v9, v11
	v_cndmask_b32_e64 v11, v19, v18, s[42:43]
	s_waitcnt lgkmcnt(1)
	v_add_f32_e32 v11, v11, v13
	v_cndmask_b32_e64 v13, v16, v20, s[42:43]
	v_cndmask_b32_e64 v16, v20, v16, s[42:43]
	ds_swizzle_b32 v16, v16 offset:swizzle(SWAP,2)
	s_waitcnt lgkmcnt(1)
	v_add_f32_e32 v5, v17, v5
	s_waitcnt lgkmcnt(0)
	v_add_f32_e32 v13, v13, v16
	v_cndmask_b32_e64 v16, v9, v5, s[44:45]
	v_cndmask_b32_e64 v5, v5, v9, s[44:45]
	v_cndmask_b32_e64 v9, v13, v11, s[44:45]
	v_cndmask_b32_e64 v11, v11, v13, s[44:45]
	ds_swizzle_b32 v5, v5 offset:swizzle(SWAP,4)
	ds_swizzle_b32 v11, v11 offset:swizzle(SWAP,4)
	s_waitcnt lgkmcnt(1)
	v_add_f32_e32 v5, v16, v5
	s_waitcnt lgkmcnt(0)
	v_add_f32_e32 v9, v9, v11
	v_cndmask_b32_e64 v11, v9, v5, s[46:47]
	v_cndmask_b32_e64 v5, v5, v9, s[46:47]
	ds_swizzle_b32 v5, v5 offset:swizzle(SWAP,8)
	s_waitcnt lgkmcnt(0)
	v_add_f32_e32 v5, v11, v5
	ds_swizzle_b32 v9, v5 offset:swizzle(SWAP,16)
	s_waitcnt lgkmcnt(0)
	v_add_f32_e32 v5, v5, v9
	ds_bpermute_b32 v9, v0, v5
	s_and_saveexec_b64 s[0:1], s[48:49]
	s_cbranch_execz .LBB0_549
	v_ashrrev_i32_e32 v13, 31, v12
	v_lshlrev_b64 v[12:13], 2, v[12:13]
	v_lshl_add_u64 v[16:17], s[8:9], 0, v[12:13]
	v_mov_b32_e32 v11, v132
	v_lshl_add_u64 v[12:13], s[10:11], 0, v[12:13]
	v_mov_b32_e32 v16, v148
	s_nop 0
	v_mov_b32_e32 v12, v140
	s_waitcnt lgkmcnt(0)
	v_add_f32_e32 v5, v5, v9
	v_mul_f32_e32 v5, v5, v11
	v_mul_f32_e32 v5, v3, v5
	v_mul_f32_e32 v11, 0x3d372713, v5
	v_mul_f32_e32 v11, v5, v11
	v_mul_f32_e32 v9, 0.5, v5
	v_fmac_f32_e32 v5, v5, v11
	v_mul_f32_e32 v5, 0x3f4c422a, v5
	v_add_f32_e32 v5, v5, v5
	v_mul_f32_e32 v5, 0x3fb8aa3b, v5
	v_exp_f32_e32 v5, v5
	s_nop 0
	v_add_f32_e32 v5, 1.0, v5
	v_rcp_f32_e32 v5, v5
	s_nop 0
	v_fma_f32 v5, v5, -2.0, 1.0
	v_add_f32_e32 v5, 1.0, v5
	v_mul_f32_e32 v5, v9, v5
	v_mul_f32_e32 v5, v16, v5
	v_mul_f32_e32 v5, v12, v5
	ds_write_b32 v109, v5 offset:256
.LBB0_549:
	s_or_b64 exec, exec, s[0:1]
	v_readlane_b32 s0, v8, 0
	s_lshl_b32 s0, s0, 9
	s_waitcnt lgkmcnt(0)
	s_waitcnt vmcnt(15)
	v_dot8_i32_i4 v5, v92, v73, 0
	v_dot8_i32_i4 v9, v92, v75, 0
	buffer_load_dwordx2 v[86:87], v192, s[52:55], s0 offen
	v_readlane_b32 s0, v8, 1
	s_lshl_b32 s0, s0, 9
	v_dot8_i32_i4 v5, v93, v77, v5
	v_dot8_i32_i4 v9, v93, v108, v9
	s_waitcnt vmcnt(15)
	v_dot8_i32_i4 v11, v96, v75, 0
	buffer_load_dwordx2 v[78:79], v192, s[52:55], s0 offen
	v_readlane_b32 s0, v8, 2
	s_lshl_b32 s0, s0, 9
	v_lshl_add_u32 v5, v5, 4, v9
	v_dot8_i32_i4 v9, v96, v73, 0
	v_dot8_i32_i4 v9, v97, v77, v9
	buffer_load_dwordx2 v[54:55], v192, s[52:55], s0 offen
	v_readlane_b32 s0, v8, 3
	s_lshl_b32 s0, s0, 9
	v_dot8_i32_i4 v11, v97, v108, v11
	s_waitcnt vmcnt(16)
	v_dot8_i32_i4 v90, v88, v75, 0
	v_dot8_i32_i4 v90, v89, v108, v90
	buffer_load_dwordx2 v[84:85], v192, s[52:55], s0 offen
	v_readlane_b32 s0, v8, 4
	s_lshl_b32 s0, s0, 9
	v_lshl_add_u32 v9, v9, 4, v11
	v_dot8_i32_i4 v11, v88, v73, 0
	v_dot8_i32_i4 v11, v89, v77, v11
	buffer_load_dwordx2 v[50:51], v192, s[52:55], s0 offen
	v_readlane_b32 s0, v8, 5
	s_lshl_b32 s0, s0, 9
	s_waitcnt vmcnt(17)
	v_dot8_i32_i4 v88, v98, v73, 0
	v_dot8_i32_i4 v89, v98, v75, 0
	buffer_load_dwordx2 v[42:43], v192, s[52:55], s0 offen
	v_readlane_b32 s0, v8, 6
	s_lshl_b32 s0, s0, 9
	v_dot8_i32_i4 v88, v99, v77, v88
	v_dot8_i32_i4 v89, v99, v108, v89
	v_lshl_add_u32 v11, v11, 4, v90
	buffer_load_dwordx2 v[38:39], v192, s[52:55], s0 offen
	v_readlane_b32 s0, v8, 7
	s_lshl_b32 s0, s0, 9
	v_lshl_add_u32 v88, v88, 4, v89
	s_waitcnt vmcnt(18)
	v_dot8_i32_i4 v89, v82, v73, 0
	v_dot8_i32_i4 v90, v82, v75, 0
	buffer_load_dwordx2 v[48:49], v192, s[52:55], s0 offen
	v_readlane_b32 s0, v8, 8
	s_lshl_b32 s0, s0, 9
	v_dot8_i32_i4 v89, v83, v77, v89
	v_dot8_i32_i4 v90, v83, v108, v90
	s_waitcnt vmcnt(18)
	v_dot8_i32_i4 v83, v56, v73, 0
	buffer_load_dwordx2 v[34:35], v192, s[52:55], s0 offen
	v_readlane_b32 s0, v8, 9
	s_lshl_b32 s0, s0, 9
	v_lshl_add_u32 v82, v89, 4, v90
	v_dot8_i32_i4 v89, v56, v75, 0
	v_dot8_i32_i4 v83, v57, v77, v83
	buffer_load_dwordx2 v[26:27], v192, s[52:55], s0 offen
	v_readlane_b32 s0, v8, 10
	s_lshl_b32 s0, s0, 9
	v_dot8_i32_i4 v89, v57, v108, v89
	s_waitcnt vmcnt(19)
	v_dot8_i32_i4 v57, v52, v73, 0
	v_dot8_i32_i4 v57, v53, v77, v57
	buffer_load_dwordx2 v[22:23], v192, s[52:55], s0 offen
	v_readlane_b32 s0, v8, 11
	s_lshl_b32 s0, s0, 9
	v_lshl_add_u32 v56, v83, 4, v89
	v_dot8_i32_i4 v83, v52, v75, 0
	v_dot8_i32_i4 v83, v53, v108, v83
	buffer_load_dwordx2 v[30:31], v192, s[52:55], s0 offen
	v_readlane_b32 s0, v8, 12
	s_lshl_b32 s0, s0, 9
	v_lshl_add_u32 v52, v57, 4, v83
	s_waitcnt vmcnt(20)
	v_dot8_i32_i4 v53, v80, v73, 0
	buffer_load_dwordx2 v[20:21], v192, s[52:55], s0 offen
	v_readlane_b32 s0, v8, 13
	s_lshl_b32 s0, s0, 9
	v_dot8_i32_i4 v57, v80, v75, 0
	v_dot8_i32_i4 v53, v81, v77, v53
	v_dot8_i32_i4 v57, v81, v108, v57
	buffer_load_dwordx2 v[16:17], v192, s[52:55], s0 offen
	v_readlane_b32 s0, v8, 14
	s_lshl_b32 s0, s0, 9
	v_lshl_add_u32 v53, v53, 4, v57
	s_waitcnt vmcnt(21)
	v_dot8_i32_i4 v57, v46, v73, 0
	v_dot8_i32_i4 v80, v46, v75, 0
	buffer_load_dwordx2 v[12:13], v192, s[52:55], s0 offen
	v_readlane_b32 s0, v8, 15
	s_lshl_b32 s0, s0, 9
	v_dot8_i32_i4 v57, v47, v77, v57
	v_dot8_i32_i4 v80, v47, v108, v80
	s_waitcnt vmcnt(21)
	v_dot8_i32_i4 v47, v40, v73, 0
	buffer_load_dwordx2 v[18:19], v192, s[52:55], s0 offen
	v_lshl_add_u32 v46, v57, 4, v80
	v_dot8_i32_i4 v57, v40, v75, 0
	v_dot8_i32_i4 v47, v41, v77, v47
	v_dot8_i32_i4 v57, v41, v108, v57
	s_waitcnt vmcnt(21)
	v_dot8_i32_i4 v41, v36, v73, 0
	v_dot8_i32_i4 v41, v37, v77, v41
	v_lshl_add_u32 v40, v47, 4, v57
	v_dot8_i32_i4 v47, v36, v75, 0
	v_dot8_i32_i4 v47, v37, v108, v47
	s_waitcnt vmcnt(20)
	v_dot8_i32_i4 v37, v44, v73, 0
	v_dot8_i32_i4 v37, v45, v77, v37
	v_lshl_add_u32 v36, v41, 4, v47
	v_dot8_i32_i4 v41, v44, v75, 0
	v_dot8_i32_i4 v41, v45, v108, v41
	s_waitcnt vmcnt(19)
	v_dot8_i32_i4 v44, v32, v75, 0
	v_dot8_i32_i4 v44, v33, v108, v44
	v_lshl_add_u32 v37, v37, 4, v41
	v_dot8_i32_i4 v41, v32, v73, 0
	v_dot8_i32_i4 v41, v33, v77, v41
	s_waitcnt vmcnt(18)
	v_dot8_i32_i4 v33, v24, v73, 0
	v_dot8_i32_i4 v33, v25, v77, v33
	v_lshl_add_u32 v32, v41, 4, v44
	v_dot8_i32_i4 v41, v24, v75, 0
	v_dot8_i32_i4 v41, v25, v108, v41
	s_waitcnt vmcnt(17)
	v_dot8_i32_i4 v25, v14, v73, 0
	v_cvt_f32_i32_e32 v5, v5
	v_lshl_add_u32 v24, v33, 4, v41
	v_dot8_i32_i4 v33, v14, v75, 0
	v_cvt_f32_i32_e32 v9, v9
	v_dot8_i32_i4 v25, v15, v77, v25
	v_dot8_i32_i4 v33, v15, v108, v33
	s_waitcnt vmcnt(16)
	v_dot8_i32_i4 v15, v28, v73, 0
	v_dot8_i32_i4 v15, v29, v77, v15
	v_lshl_add_u32 v14, v25, 4, v33
	v_dot8_i32_i4 v25, v28, v75, 0
	v_dot8_i32_i4 v25, v29, v108, v25
	v_cvt_f32_i32_e32 v11, v11
	v_cvt_f32_i32_e32 v88, v88
	v_cvt_f32_i32_e32 v82, v82
	v_lshl_add_u32 v15, v15, 4, v25
	v_cndmask_b32_e64 v25, v9, v5, s[40:41]
	v_cndmask_b32_e64 v5, v5, v9, s[40:41]
	ds_swizzle_b32 v5, v5 offset:swizzle(SWAP,1)
	v_cvt_f32_i32_e32 v56, v56
	v_cvt_f32_i32_e32 v52, v52
	v_cvt_f32_i32_e32 v53, v53
	v_cvt_f32_i32_e32 v46, v46
	v_cvt_f32_i32_e32 v40, v40
	v_cvt_f32_i32_e32 v36, v36
	v_cvt_f32_i32_e32 v37, v37
	v_cndmask_b32_e64 v9, v88, v11, s[40:41]
	v_cndmask_b32_e64 v11, v11, v88, s[40:41]
	s_waitcnt lgkmcnt(0)
	v_add_f32_e32 v5, v25, v5
	ds_swizzle_b32 v11, v11 offset:swizzle(SWAP,1)
	v_cndmask_b32_e64 v25, v82, v56, s[40:41]
	ds_swizzle_b32 v25, v25 offset:swizzle(SWAP,1)
	v_cndmask_b32_e64 v28, v52, v53, s[40:41]
	ds_swizzle_b32 v28, v28 offset:swizzle(SWAP,1)
	v_cndmask_b32_e64 v29, v46, v40, s[40:41]
	ds_swizzle_b32 v29, v29 offset:swizzle(SWAP,1)
	v_cndmask_b32_e64 v33, v36, v37, s[40:41]
	ds_swizzle_b32 v33, v33 offset:swizzle(SWAP,1)
	v_cvt_f32_i32_e32 v32, v32
	v_cvt_f32_i32_e32 v24, v24
	v_cvt_f32_i32_e32 v14, v14
	v_cvt_f32_i32_e32 v15, v15
	s_waitcnt lgkmcnt(4)
	v_add_f32_e32 v9, v9, v11
	v_cndmask_b32_e64 v11, v56, v82, s[40:41]
	s_waitcnt lgkmcnt(3)
	v_add_f32_e32 v11, v11, v25
	v_cndmask_b32_e64 v25, v53, v52, s[40:41]
	s_waitcnt lgkmcnt(2)
	v_add_f32_e32 v25, v25, v28
	v_cndmask_b32_e64 v28, v40, v46, s[40:41]
	s_waitcnt lgkmcnt(1)
	v_add_f32_e32 v28, v28, v29
	v_cndmask_b32_e64 v29, v37, v36, s[40:41]
	s_waitcnt lgkmcnt(0)
	v_add_f32_e32 v29, v29, v33
	v_cndmask_b32_e64 v33, v24, v32, s[40:41]
	v_cndmask_b32_e64 v24, v32, v24, s[40:41]
	v_cndmask_b32_e64 v32, v15, v14, s[40:41]
	v_cndmask_b32_e64 v14, v14, v15, s[40:41]
	v_cndmask_b32_e64 v15, v9, v5, s[42:43]
	v_cndmask_b32_e64 v5, v5, v9, s[42:43]
	ds_swizzle_b32 v5, v5 offset:swizzle(SWAP,2)
	v_cndmask_b32_e64 v9, v25, v11, s[42:43]
	v_cndmask_b32_e64 v11, v11, v25, s[42:43]
	ds_swizzle_b32 v24, v24 offset:swizzle(SWAP,1)
	ds_swizzle_b32 v14, v14 offset:swizzle(SWAP,1)
	s_waitcnt lgkmcnt(2)
	v_add_f32_e32 v5, v15, v5
	ds_swizzle_b32 v11, v11 offset:swizzle(SWAP,2)
	v_cndmask_b32_e64 v15, v28, v29, s[42:43]
	ds_swizzle_b32 v15, v15 offset:swizzle(SWAP,2)
	s_waitcnt lgkmcnt(3)
	v_add_f32_e32 v24, v33, v24
	s_waitcnt lgkmcnt(2)
	v_add_f32_e32 v14, v32, v14
	s_waitcnt lgkmcnt(1)
	v_add_f32_e32 v9, v9, v11
	v_cndmask_b32_e64 v11, v29, v28, s[42:43]
	s_waitcnt lgkmcnt(0)
	v_add_f32_e32 v11, v11, v15
	v_cndmask_b32_e64 v15, v14, v24, s[42:43]
	v_cndmask_b32_e64 v14, v24, v14, s[42:43]
	ds_swizzle_b32 v14, v14 offset:swizzle(SWAP,2)
	s_waitcnt lgkmcnt(0)
	v_add_f32_e32 v14, v15, v14
	v_cndmask_b32_e64 v15, v9, v5, s[44:45]
	v_cndmask_b32_e64 v5, v5, v9, s[44:45]
	v_cndmask_b32_e64 v9, v14, v11, s[44:45]
	v_cndmask_b32_e64 v11, v11, v14, s[44:45]
	ds_swizzle_b32 v5, v5 offset:swizzle(SWAP,4)
	ds_swizzle_b32 v11, v11 offset:swizzle(SWAP,4)
	s_waitcnt lgkmcnt(1)
	v_add_f32_e32 v5, v15, v5
	s_waitcnt lgkmcnt(0)
	v_add_f32_e32 v9, v9, v11
	v_cndmask_b32_e64 v11, v9, v5, s[46:47]
	v_cndmask_b32_e64 v5, v5, v9, s[46:47]
	ds_swizzle_b32 v5, v5 offset:swizzle(SWAP,8)
	s_waitcnt lgkmcnt(0)
	v_add_f32_e32 v5, v11, v5
	ds_swizzle_b32 v9, v5 offset:swizzle(SWAP,16)
	s_waitcnt lgkmcnt(0)
	v_add_f32_e32 v5, v5, v9
	ds_bpermute_b32 v9, v0, v5
	s_and_saveexec_b64 s[0:1], s[48:49]
	s_cbranch_execz .LBB0_551
	v_ashrrev_i32_e32 v11, 31, v10
	v_lshlrev_b64 v[10:11], 2, v[10:11]
	v_lshl_add_u64 v[14:15], s[8:9], 0, v[10:11]
	v_mov_b32_e32 v14, v133
	v_lshl_add_u64 v[10:11], s[10:11], 0, v[10:11]
	v_mov_b32_e32 v15, v149
	s_nop 0
	v_mov_b32_e32 v10, v141
	s_waitcnt lgkmcnt(0)
	v_add_f32_e32 v5, v5, v9
	v_mul_f32_e32 v5, v5, v14
	v_mul_f32_e32 v5, v3, v5
	v_mul_f32_e32 v11, 0x3d372713, v5
	v_mul_f32_e32 v11, v5, v11
	v_mul_f32_e32 v9, 0.5, v5
	v_fmac_f32_e32 v5, v5, v11
	v_mul_f32_e32 v5, 0x3f4c422a, v5
	v_add_f32_e32 v5, v5, v5
	v_mul_f32_e32 v5, 0x3fb8aa3b, v5
	v_exp_f32_e32 v5, v5
	s_nop 0
	v_add_f32_e32 v5, 1.0, v5
	v_rcp_f32_e32 v5, v5
	s_nop 0
	v_fma_f32 v5, v5, -2.0, 1.0
	v_add_f32_e32 v5, 1.0, v5
	v_mul_f32_e32 v5, v9, v5
	v_mul_f32_e32 v5, v15, v5
	v_mul_f32_e32 v5, v10, v5
	ds_write_b32 v109, v5 offset:320
.LBB0_551:
	s_or_b64 exec, exec, s[0:1]
	s_waitcnt lgkmcnt(0)
	v_readlane_b32 s0, v4, 0
	s_waitcnt vmcnt(15)
	v_dot8_i32_i4 v5, v86, v73, 0
	v_dot8_i32_i4 v9, v86, v75, 0
	s_lshl_b32 s0, s0, 9
	v_dot8_i32_i4 v5, v87, v77, v5
	v_dot8_i32_i4 v9, v87, v108, v9
	buffer_load_dwordx2 v[88:89], v192, s[52:55], s0 offen
	v_readlane_b32 s0, v4, 1
	s_nop 0
	v_lshl_add_u32 v5, v5, 4, v9
	s_lshl_b32 s0, s0, 9
	s_waitcnt vmcnt(15)
	v_dot8_i32_i4 v9, v78, v73, 0
	v_dot8_i32_i4 v86, v78, v75, 0
	buffer_load_dwordx2 v[90:91], v192, s[52:55], s0 offen
	v_readlane_b32 s0, v4, 2
	v_dot8_i32_i4 v9, v79, v77, v9
	v_dot8_i32_i4 v86, v79, v108, v86
	s_lshl_b32 s0, s0, 9
	s_waitcnt vmcnt(15)
	v_dot8_i32_i4 v78, v54, v73, 0
	v_dot8_i32_i4 v79, v54, v75, 0
	buffer_load_dwordx2 v[82:83], v192, s[52:55], s0 offen
	v_readlane_b32 s0, v4, 3
	v_dot8_i32_i4 v78, v55, v77, v78
	v_dot8_i32_i4 v79, v55, v108, v79
	s_lshl_b32 s0, s0, 9
	s_waitcnt vmcnt(15)
	v_dot8_i32_i4 v55, v84, v73, 0
	v_lshl_add_u32 v54, v78, 4, v79
	buffer_load_dwordx2 v[92:93], v192, s[52:55], s0 offen
	v_readlane_b32 s0, v4, 4
	v_dot8_i32_i4 v78, v84, v75, 0
	s_lshl_b32 s0, s0, 9
	v_dot8_i32_i4 v55, v85, v77, v55
	v_dot8_i32_i4 v78, v85, v108, v78
	buffer_load_dwordx2 v[80:81], v192, s[52:55], s0 offen
	v_readlane_b32 s0, v4, 5
	s_nop 0
	v_lshl_add_u32 v55, v55, 4, v78
	s_lshl_b32 s0, s0, 9
	s_waitcnt vmcnt(16)
	v_dot8_i32_i4 v78, v50, v73, 0
	v_dot8_i32_i4 v79, v50, v75, 0
	buffer_load_dwordx2 v[52:53], v192, s[52:55], s0 offen
	v_readlane_b32 s0, v4, 6
	v_dot8_i32_i4 v78, v51, v77, v78
	v_dot8_i32_i4 v79, v51, v108, v79
	s_lshl_b32 s0, s0, 9
	s_waitcnt vmcnt(16)
	v_dot8_i32_i4 v51, v42, v73, 0
	v_lshl_add_u32 v50, v78, 4, v79
	buffer_load_dwordx2 v[46:47], v192, s[52:55], s0 offen
	v_readlane_b32 s0, v4, 7
	v_dot8_i32_i4 v78, v42, v75, 0
	s_lshl_b32 s0, s0, 9
	v_dot8_i32_i4 v51, v43, v77, v51
	v_dot8_i32_i4 v78, v43, v108, v78
	buffer_load_dwordx2 v[56:57], v192, s[52:55], s0 offen
	v_readlane_b32 s0, v4, 8
	s_nop 0
	v_lshl_add_u32 v42, v51, 4, v78
	s_lshl_b32 s0, s0, 9
	s_waitcnt vmcnt(17)
	v_dot8_i32_i4 v43, v38, v73, 0
	v_dot8_i32_i4 v51, v38, v75, 0
	buffer_load_dwordx2 v[44:45], v192, s[52:55], s0 offen
	v_readlane_b32 s0, v4, 9
	v_dot8_i32_i4 v43, v39, v77, v43
	v_dot8_i32_i4 v51, v39, v108, v51
	s_lshl_b32 s0, s0, 9
	s_waitcnt vmcnt(17)
	v_dot8_i32_i4 v39, v48, v73, 0
	v_lshl_add_u32 v38, v43, 4, v51
	buffer_load_dwordx2 v[36:37], v192, s[52:55], s0 offen
	v_readlane_b32 s0, v4, 10
	v_dot8_i32_i4 v43, v48, v75, 0
	s_lshl_b32 s0, s0, 9
	v_dot8_i32_i4 v39, v49, v77, v39
	v_dot8_i32_i4 v43, v49, v108, v43
	buffer_load_dwordx2 v[32:33], v192, s[52:55], s0 offen
	v_readlane_b32 s0, v4, 11
	s_nop 0
	v_lshl_add_u32 v39, v39, 4, v43
	s_lshl_b32 s0, s0, 9
	s_waitcnt vmcnt(18)
	v_dot8_i32_i4 v43, v34, v73, 0
	v_dot8_i32_i4 v48, v34, v75, 0
	buffer_load_dwordx2 v[40:41], v192, s[52:55], s0 offen
	v_readlane_b32 s0, v4, 12
	v_dot8_i32_i4 v43, v35, v77, v43
	v_dot8_i32_i4 v48, v35, v108, v48
	s_lshl_b32 s0, s0, 9
	s_waitcnt vmcnt(18)
	v_dot8_i32_i4 v35, v26, v73, 0
	v_lshl_add_u32 v34, v43, 4, v48
	buffer_load_dwordx2 v[28:29], v192, s[52:55], s0 offen
	v_readlane_b32 s0, v4, 13
	v_dot8_i32_i4 v43, v26, v75, 0
	s_lshl_b32 s0, s0, 9
	v_dot8_i32_i4 v35, v27, v77, v35
	v_dot8_i32_i4 v43, v27, v108, v43
	buffer_load_dwordx2 v[14:15], v192, s[52:55], s0 offen
	v_readlane_b32 s0, v4, 14
	s_nop 0
	v_lshl_add_u32 v26, v35, 4, v43
	s_lshl_b32 s0, s0, 9
	s_waitcnt vmcnt(19)
	v_dot8_i32_i4 v27, v22, v73, 0
	v_dot8_i32_i4 v35, v22, v75, 0
	buffer_load_dwordx2 v[10:11], v192, s[52:55], s0 offen
	v_readlane_b32 s0, v4, 15
	v_dot8_i32_i4 v27, v23, v77, v27
	v_dot8_i32_i4 v35, v23, v108, v35
	s_lshl_b32 s0, s0, 9
	s_waitcnt vmcnt(19)
	v_dot8_i32_i4 v23, v30, v73, 0
	v_lshl_add_u32 v22, v27, 4, v35
	buffer_load_dwordx2 v[24:25], v192, s[52:55], s0 offen
	v_dot8_i32_i4 v27, v30, v75, 0
	v_dot8_i32_i4 v23, v31, v77, v23
	v_dot8_i32_i4 v27, v31, v108, v27
	s_waitcnt vmcnt(19)
	v_dot8_i32_i4 v30, v20, v75, 0
	v_dot8_i32_i4 v30, v21, v108, v30
	v_lshl_add_u32 v23, v23, 4, v27
	v_dot8_i32_i4 v27, v20, v73, 0
	v_dot8_i32_i4 v27, v21, v77, v27
	s_waitcnt vmcnt(18)
	v_dot8_i32_i4 v21, v16, v73, 0
	v_dot8_i32_i4 v21, v17, v77, v21
	v_lshl_add_u32 v20, v27, 4, v30
	v_dot8_i32_i4 v27, v16, v75, 0
	v_dot8_i32_i4 v27, v17, v108, v27
	v_lshl_add_u32 v9, v9, 4, v86
	s_waitcnt vmcnt(17)
	v_dot8_i32_i4 v17, v12, v73, 0
	v_lshl_add_u32 v16, v21, 4, v27
	v_dot8_i32_i4 v21, v12, v75, 0
	v_cvt_f32_i32_e32 v5, v5
	v_cvt_f32_i32_e32 v9, v9
	v_dot8_i32_i4 v17, v13, v77, v17
	v_dot8_i32_i4 v21, v13, v108, v21
	s_waitcnt vmcnt(16)
	v_dot8_i32_i4 v13, v18, v73, 0
	v_dot8_i32_i4 v13, v19, v77, v13
	v_lshl_add_u32 v12, v17, 4, v21
	v_dot8_i32_i4 v17, v18, v75, 0
	v_dot8_i32_i4 v17, v19, v108, v17
	v_cvt_f32_i32_e32 v54, v54
	v_cvt_f32_i32_e32 v55, v55
	v_cvt_f32_i32_e32 v50, v50
	v_lshl_add_u32 v13, v13, 4, v17
	v_cndmask_b32_e64 v17, v9, v5, s[40:41]
	v_cndmask_b32_e64 v5, v5, v9, s[40:41]
	ds_swizzle_b32 v5, v5 offset:swizzle(SWAP,1)
	v_cvt_f32_i32_e32 v42, v42
	v_cvt_f32_i32_e32 v38, v38
	v_cvt_f32_i32_e32 v39, v39
	v_cvt_f32_i32_e32 v34, v34
	v_cvt_f32_i32_e32 v26, v26
	s_waitcnt lgkmcnt(0)
	v_add_f32_e32 v5, v17, v5
	v_cndmask_b32_e64 v17, v54, v55, s[40:41]
	ds_swizzle_b32 v17, v17 offset:swizzle(SWAP,1)
	v_cndmask_b32_e64 v18, v50, v42, s[40:41]
	ds_swizzle_b32 v18, v18 offset:swizzle(SWAP,1)
	v_cndmask_b32_e64 v19, v38, v39, s[40:41]
	ds_swizzle_b32 v19, v19 offset:swizzle(SWAP,1)
	v_cndmask_b32_e64 v21, v34, v26, s[40:41]
	ds_swizzle_b32 v21, v21 offset:swizzle(SWAP,1)
	v_cvt_f32_i32_e32 v22, v22
	v_cvt_f32_i32_e32 v23, v23
	v_cndmask_b32_e64 v9, v55, v54, s[40:41]
	s_waitcnt lgkmcnt(3)
	v_add_f32_e32 v9, v9, v17
	v_cndmask_b32_e64 v17, v42, v50, s[40:41]
	s_waitcnt lgkmcnt(2)
	v_add_f32_e32 v17, v17, v18
	v_cndmask_b32_e64 v18, v39, v38, s[40:41]
	s_waitcnt lgkmcnt(1)
	v_add_f32_e32 v18, v18, v19
	v_cndmask_b32_e64 v19, v26, v34, s[40:41]
	s_waitcnt lgkmcnt(0)
	v_add_f32_e32 v19, v19, v21
	v_cndmask_b32_e64 v21, v23, v22, s[40:41]
	v_cndmask_b32_e64 v22, v22, v23, s[40:41]
	ds_swizzle_b32 v22, v22 offset:swizzle(SWAP,1)
	v_cvt_f32_i32_e32 v20, v20
	v_cvt_f32_i32_e32 v16, v16
	v_cvt_f32_i32_e32 v12, v12
	v_cvt_f32_i32_e32 v13, v13
	s_waitcnt lgkmcnt(0)
	v_add_f32_e32 v21, v21, v22
	v_cndmask_b32_e64 v22, v16, v20, s[40:41]
	v_cndmask_b32_e64 v16, v20, v16, s[40:41]
	v_cndmask_b32_e64 v20, v13, v12, s[40:41]
	v_cndmask_b32_e64 v12, v12, v13, s[40:41]
	v_cndmask_b32_e64 v13, v9, v5, s[42:43]
	v_cndmask_b32_e64 v5, v5, v9, s[42:43]
	ds_swizzle_b32 v5, v5 offset:swizzle(SWAP,2)
	ds_swizzle_b32 v16, v16 offset:swizzle(SWAP,1)
	ds_swizzle_b32 v12, v12 offset:swizzle(SWAP,1)
	v_cndmask_b32_e64 v9, v18, v17, s[42:43]
	s_waitcnt lgkmcnt(2)
	v_add_f32_e32 v5, v13, v5
	v_cndmask_b32_e64 v13, v17, v18, s[42:43]
	ds_swizzle_b32 v13, v13 offset:swizzle(SWAP,2)
	v_cndmask_b32_e64 v17, v19, v21, s[42:43]
	ds_swizzle_b32 v17, v17 offset:swizzle(SWAP,2)
	s_waitcnt lgkmcnt(3)
	v_add_f32_e32 v16, v22, v16
	s_waitcnt lgkmcnt(2)
	v_add_f32_e32 v12, v20, v12
	s_waitcnt lgkmcnt(1)
	v_add_f32_e32 v9, v9, v13
	v_cndmask_b32_e64 v13, v21, v19, s[42:43]
	s_waitcnt lgkmcnt(0)
	v_add_f32_e32 v13, v13, v17
	v_cndmask_b32_e64 v17, v12, v16, s[42:43]
	v_cndmask_b32_e64 v12, v16, v12, s[42:43]
	ds_swizzle_b32 v12, v12 offset:swizzle(SWAP,2)
	v_cndmask_b32_e64 v16, v9, v5, s[44:45]
	v_cndmask_b32_e64 v5, v5, v9, s[44:45]
	ds_swizzle_b32 v5, v5 offset:swizzle(SWAP,4)
	s_waitcnt lgkmcnt(1)
	v_add_f32_e32 v12, v17, v12
	v_cndmask_b32_e64 v9, v12, v13, s[44:45]
	v_cndmask_b32_e64 v12, v13, v12, s[44:45]
	ds_swizzle_b32 v12, v12 offset:swizzle(SWAP,4)
	s_waitcnt lgkmcnt(1)
	v_add_f32_e32 v5, v16, v5
	s_waitcnt lgkmcnt(0)
	v_add_f32_e32 v9, v9, v12
	v_cndmask_b32_e64 v12, v9, v5, s[46:47]
	v_cndmask_b32_e64 v5, v5, v9, s[46:47]
	ds_swizzle_b32 v5, v5 offset:swizzle(SWAP,8)
	s_waitcnt lgkmcnt(0)
	v_add_f32_e32 v5, v12, v5
	ds_swizzle_b32 v9, v5 offset:swizzle(SWAP,16)
	s_waitcnt lgkmcnt(0)
	v_add_f32_e32 v5, v5, v9
	ds_bpermute_b32 v12, v0, v5
	s_and_saveexec_b64 s[0:1], s[48:49]
	s_cbranch_execz .LBB0_553
	v_ashrrev_i32_e32 v9, 31, v8
	v_lshlrev_b64 v[8:9], 2, v[8:9]
	v_lshl_add_u64 v[16:17], s[8:9], 0, v[8:9]
	v_mov_b32_e32 v13, v134
	v_lshl_add_u64 v[8:9], s[10:11], 0, v[8:9]
	v_mov_b32_e32 v16, v150
	s_nop 0
	v_mov_b32_e32 v8, v142
	s_waitcnt lgkmcnt(0)
	v_add_f32_e32 v5, v5, v12
	v_mul_f32_e32 v5, v5, v13
	v_mul_f32_e32 v5, v3, v5
	v_mul_f32_e32 v12, 0x3d372713, v5
	v_mul_f32_e32 v12, v5, v12
	v_mul_f32_e32 v9, 0.5, v5
	v_fmac_f32_e32 v5, v5, v12
	v_mul_f32_e32 v5, 0x3f4c422a, v5
	v_add_f32_e32 v5, v5, v5
	v_mul_f32_e32 v5, 0x3fb8aa3b, v5
	v_exp_f32_e32 v5, v5
	s_nop 0
	v_add_f32_e32 v5, 1.0, v5
	v_rcp_f32_e32 v5, v5
	s_nop 0
	v_fma_f32 v5, v5, -2.0, 1.0
	v_add_f32_e32 v5, 1.0, v5
	v_mul_f32_e32 v5, v9, v5
	v_mul_f32_e32 v5, v16, v5
	v_mul_f32_e32 v5, v8, v5
	ds_write_b32 v109, v5 offset:384
.LBB0_553:
	s_or_b64 exec, exec, s[0:1]
	s_waitcnt vmcnt(15)
	v_dot8_i32_i4 v5, v88, v73, 0
	v_dot8_i32_i4 v8, v88, v75, 0
	v_dot8_i32_i4 v5, v89, v77, v5
	v_dot8_i32_i4 v8, v89, v108, v8
	s_waitcnt vmcnt(14)
	v_dot8_i32_i4 v9, v90, v75, 0
	v_dot8_i32_i4 v9, v91, v108, v9
	v_lshl_add_u32 v5, v5, 4, v8
	v_dot8_i32_i4 v8, v90, v73, 0
	v_dot8_i32_i4 v8, v91, v77, v8
	s_waitcnt lgkmcnt(0)
	s_waitcnt vmcnt(13)
	v_dot8_i32_i4 v12, v82, v75, 0
	v_dot8_i32_i4 v12, v83, v108, v12
	v_lshl_add_u32 v8, v8, 4, v9
	v_dot8_i32_i4 v9, v82, v73, 0
	v_dot8_i32_i4 v9, v83, v77, v9
	s_waitcnt vmcnt(12)
	v_dot8_i32_i4 v13, v92, v75, 0
	v_dot8_i32_i4 v13, v93, v108, v13
	v_lshl_add_u32 v9, v9, 4, v12
	v_dot8_i32_i4 v12, v92, v73, 0
	v_dot8_i32_i4 v12, v93, v77, v12
	s_waitcnt vmcnt(11)
	v_dot8_i32_i4 v16, v80, v75, 0
	v_dot8_i32_i4 v16, v81, v108, v16
	v_lshl_add_u32 v12, v12, 4, v13
	v_dot8_i32_i4 v13, v80, v73, 0
	v_dot8_i32_i4 v13, v81, v77, v13
	s_waitcnt vmcnt(10)
	v_dot8_i32_i4 v17, v52, v75, 0
	v_dot8_i32_i4 v17, v53, v108, v17
	v_lshl_add_u32 v13, v13, 4, v16
	v_dot8_i32_i4 v16, v52, v73, 0
	v_dot8_i32_i4 v16, v53, v77, v16
	s_waitcnt vmcnt(9)
	v_dot8_i32_i4 v18, v46, v75, 0
	v_dot8_i32_i4 v18, v47, v108, v18
	v_lshl_add_u32 v16, v16, 4, v17
	v_dot8_i32_i4 v17, v46, v73, 0
	v_dot8_i32_i4 v17, v47, v77, v17
	s_waitcnt vmcnt(8)
	v_dot8_i32_i4 v19, v56, v75, 0
	v_dot8_i32_i4 v19, v57, v108, v19
	v_lshl_add_u32 v17, v17, 4, v18
	v_dot8_i32_i4 v18, v56, v73, 0
	v_dot8_i32_i4 v18, v57, v77, v18
	s_waitcnt vmcnt(7)
	v_dot8_i32_i4 v20, v44, v75, 0
	v_dot8_i32_i4 v20, v45, v108, v20
	v_lshl_add_u32 v18, v18, 4, v19
	v_dot8_i32_i4 v19, v44, v73, 0
	v_dot8_i32_i4 v19, v45, v77, v19
	s_waitcnt vmcnt(6)
	v_dot8_i32_i4 v21, v36, v75, 0
	v_dot8_i32_i4 v21, v37, v108, v21
	v_lshl_add_u32 v19, v19, 4, v20
	v_dot8_i32_i4 v20, v36, v73, 0
	v_dot8_i32_i4 v20, v37, v77, v20
	s_waitcnt vmcnt(5)
	v_dot8_i32_i4 v22, v32, v75, 0
	v_dot8_i32_i4 v22, v33, v108, v22
	v_lshl_add_u32 v20, v20, 4, v21
	v_dot8_i32_i4 v21, v32, v73, 0
	v_dot8_i32_i4 v21, v33, v77, v21
	s_waitcnt vmcnt(4)
	v_dot8_i32_i4 v23, v40, v75, 0
	v_dot8_i32_i4 v23, v41, v108, v23
	v_lshl_add_u32 v21, v21, 4, v22
	v_dot8_i32_i4 v22, v40, v73, 0
	v_dot8_i32_i4 v22, v41, v77, v22
	s_waitcnt vmcnt(3)
	v_dot8_i32_i4 v26, v28, v75, 0
	v_dot8_i32_i4 v26, v29, v108, v26
	v_lshl_add_u32 v22, v22, 4, v23
	v_dot8_i32_i4 v23, v28, v73, 0
	v_dot8_i32_i4 v23, v29, v77, v23
	s_waitcnt vmcnt(2)
	v_dot8_i32_i4 v27, v14, v75, 0
	v_dot8_i32_i4 v27, v15, v108, v27
	v_lshl_add_u32 v23, v23, 4, v26
	v_dot8_i32_i4 v26, v14, v73, 0
	v_dot8_i32_i4 v26, v15, v77, v26
	s_waitcnt vmcnt(1)
	v_dot8_i32_i4 v15, v10, v73, 0
	v_cvt_f32_i32_e32 v5, v5
	v_lshl_add_u32 v14, v26, 4, v27
	v_dot8_i32_i4 v26, v10, v75, 0
	v_cvt_f32_i32_e32 v8, v8
	v_cvt_f32_i32_e32 v9, v9
	v_cvt_f32_i32_e32 v12, v12
	v_dot8_i32_i4 v15, v11, v77, v15
	v_dot8_i32_i4 v26, v11, v108, v26
	s_waitcnt vmcnt(0)
	v_dot8_i32_i4 v11, v24, v73, 0
	v_dot8_i32_i4 v11, v25, v77, v11
	v_lshl_add_u32 v10, v15, 4, v26
	v_dot8_i32_i4 v15, v24, v75, 0
	v_dot8_i32_i4 v15, v25, v108, v15
	v_cvt_f32_i32_e32 v13, v13
	v_cvt_f32_i32_e32 v16, v16
	v_cvt_f32_i32_e32 v17, v17
	v_lshl_add_u32 v11, v11, 4, v15
	v_cndmask_b32_e64 v15, v8, v5, s[40:41]
	v_cndmask_b32_e64 v5, v5, v8, s[40:41]
	v_cndmask_b32_e64 v8, v9, v12, s[40:41]
	ds_swizzle_b32 v8, v8 offset:swizzle(SWAP,1)
	v_cvt_f32_i32_e32 v18, v18
	ds_swizzle_b32 v5, v5 offset:swizzle(SWAP,1)
	v_cvt_f32_i32_e32 v19, v19
	v_cvt_f32_i32_e32 v20, v20
	v_cvt_f32_i32_e32 v21, v21
	v_cvt_f32_i32_e32 v22, v22
	v_cndmask_b32_e64 v9, v12, v9, s[40:41]
	v_cndmask_b32_e64 v24, v13, v16, s[40:41]
	s_waitcnt lgkmcnt(1)
	v_add_f32_e32 v8, v9, v8
	v_cndmask_b32_e64 v9, v16, v13, s[40:41]
	v_cndmask_b32_e64 v13, v17, v18, s[40:41]
	s_waitcnt lgkmcnt(0)
	v_add_f32_e32 v5, v15, v5
	ds_swizzle_b32 v13, v13 offset:swizzle(SWAP,1)
	v_cndmask_b32_e64 v15, v19, v20, s[40:41]
	ds_swizzle_b32 v15, v15 offset:swizzle(SWAP,1)
	v_cndmask_b32_e64 v16, v21, v22, s[40:41]
	ds_swizzle_b32 v16, v16 offset:swizzle(SWAP,1)
	v_cvt_f32_i32_e32 v23, v23
	v_cvt_f32_i32_e32 v14, v14
	v_cvt_f32_i32_e32 v10, v10
	v_cvt_f32_i32_e32 v11, v11
	v_cndmask_b32_e64 v12, v18, v17, s[40:41]
	s_waitcnt lgkmcnt(2)
	v_add_f32_e32 v12, v12, v13
	v_cndmask_b32_e64 v13, v20, v19, s[40:41]
	s_waitcnt lgkmcnt(1)
	v_add_f32_e32 v13, v13, v15
	v_cndmask_b32_e64 v15, v22, v21, s[40:41]
	ds_swizzle_b32 v24, v24 offset:swizzle(SWAP,1)
	s_waitcnt lgkmcnt(1)
	v_add_f32_e32 v15, v15, v16
	v_cndmask_b32_e64 v16, v14, v23, s[40:41]
	v_cndmask_b32_e64 v14, v23, v14, s[40:41]
	v_cndmask_b32_e64 v17, v10, v11, s[40:41]
	ds_swizzle_b32 v14, v14 offset:swizzle(SWAP,1)
	ds_swizzle_b32 v17, v17 offset:swizzle(SWAP,1)
	s_waitcnt lgkmcnt(2)
	v_add_f32_e32 v9, v9, v24
	v_cndmask_b32_e64 v10, v11, v10, s[40:41]
	v_cndmask_b32_e64 v18, v5, v8, s[42:43]
	s_waitcnt lgkmcnt(1)
	v_add_f32_e32 v14, v16, v14
	s_waitcnt lgkmcnt(0)
	v_add_f32_e32 v10, v10, v17
	v_cndmask_b32_e64 v5, v8, v5, s[42:43]
	v_cndmask_b32_e64 v8, v12, v9, s[42:43]
	v_cndmask_b32_e64 v9, v9, v12, s[42:43]
	ds_swizzle_b32 v9, v9 offset:swizzle(SWAP,2)
	v_cndmask_b32_e64 v11, v13, v15, s[42:43]
	v_cndmask_b32_e64 v12, v14, v10, s[42:43]
	ds_swizzle_b32 v18, v18 offset:swizzle(SWAP,2)
	ds_swizzle_b32 v11, v11 offset:swizzle(SWAP,2)
	ds_swizzle_b32 v12, v12 offset:swizzle(SWAP,2)
	s_waitcnt lgkmcnt(3)
	v_add_f32_e32 v8, v8, v9
	v_cndmask_b32_e64 v9, v15, v13, s[42:43]
	v_cndmask_b32_e64 v10, v10, v14, s[42:43]
	s_waitcnt lgkmcnt(2)
	v_add_f32_e32 v5, v5, v18
	s_waitcnt lgkmcnt(1)
	v_add_f32_e32 v9, v9, v11
	s_waitcnt lgkmcnt(0)
	v_add_f32_e32 v10, v10, v12
	v_cndmask_b32_e64 v11, v5, v8, s[44:45]
	v_cndmask_b32_e64 v12, v9, v10, s[44:45]
	ds_swizzle_b32 v11, v11 offset:swizzle(SWAP,4)
	ds_swizzle_b32 v12, v12 offset:swizzle(SWAP,4)
	v_cndmask_b32_e64 v5, v8, v5, s[44:45]
	v_cndmask_b32_e64 v8, v10, v9, s[44:45]
	s_waitcnt lgkmcnt(1)
	v_add_f32_e32 v5, v5, v11
	s_waitcnt lgkmcnt(0)
	v_add_f32_e32 v8, v8, v12
	v_cndmask_b32_e64 v9, v5, v8, s[46:47]
	ds_swizzle_b32 v9, v9 offset:swizzle(SWAP,8)
	v_cndmask_b32_e64 v5, v8, v5, s[46:47]
	s_waitcnt lgkmcnt(0)
	v_add_f32_e32 v5, v5, v9
	ds_swizzle_b32 v8, v5 offset:swizzle(SWAP,16)
	s_waitcnt lgkmcnt(0)
	v_add_f32_e32 v8, v5, v8
	ds_bpermute_b32 v0, v0, v8
	s_and_saveexec_b64 s[0:1], s[48:49]
	s_cbranch_execz .LBB0_536
	v_ashrrev_i32_e32 v5, 31, v4
	v_lshlrev_b64 v[4:5], 2, v[4:5]
	v_lshl_add_u64 v[10:11], s[8:9], 0, v[4:5]
	v_mov_b32_e32 v9, v135
	v_lshl_add_u64 v[4:5], s[10:11], 0, v[4:5]
	v_mov_b32_e32 v6, v151
	s_nop 0
	v_mov_b32_e32 v4, v143
	s_waitcnt lgkmcnt(0)
	v_add_f32_e32 v0, v8, v0
	v_mul_f32_e32 v0, v0, v9
	v_mul_f32_e32 v0, v3, v0
	v_mul_f32_e32 v5, 0x3d372713, v0
	v_mul_f32_e32 v5, v0, v5
	v_mul_f32_e32 v3, 0.5, v0
	v_fmac_f32_e32 v0, v0, v5
	v_mul_f32_e32 v0, 0x3f4c422a, v0
	v_add_f32_e32 v0, v0, v0
	v_mul_f32_e32 v0, 0x3fb8aa3b, v0
	v_exp_f32_e32 v0, v0
	s_nop 0
	v_add_f32_e32 v0, 1.0, v0
	v_rcp_f32_e32 v0, v0
	s_nop 0
	v_fma_f32 v0, v0, -2.0, 1.0
	v_add_f32_e32 v0, 1.0, v0
	v_mul_f32_e32 v0, v3, v0
	v_mul_f32_e32 v0, v6, v0
	v_mul_f32_e32 v0, v4, v0
	ds_write_b32 v109, v0 offset:448
	s_branch .LBB0_536
